# attention loop: T1 = sign x slope kept persistent (it flips once, behind the diagonal tiles): per-tile bias prep trimmed from 2 SALU + 2 VALU to 1 fma
# baseline (speedup 1.0000x reference)
; __device__ __forceinline__ void bias_init(f32x16& p0, f32x16& p1, float base, float nslope2, float nM2, int rel  ) {
;     if (rel <= -63 || rel >= 31) {
;         const float sg = (rel < 0) ? -nslope2 : nslope2, lbv = fmaf(-sg, base, nM2);
; #pragma unroll
;         for (int r = 0; r < 16; ++r) { p0[r] = fmaf((float)((r & 3) + 8 * (r >> 2)), sg, lbv); p1[r] = fmaf((float)((r & 3) + 8 * (r >> 2) + 32), sg, lbv); }
;     } else {
; #pragma unroll
;         for (int r = 0; r < 16; ++r) { const float d = base - (float)((r & 3) + 8 * (r >> 2));
;             p0[r] = fmaf(fabsf(d), nslope2, nM2); p1[r] = fmaf(fabsf(d - 32.f), nslope2, nM2); }
;     }
; }
; __device__ __forceinline__ void diff_unit(const DiffArgs& A, int b, int h, int qb, char* lds, int wv) {
;     ...
;     float l_reg = 0; f32x16 o[4] = {}; bf16x8 qr[4];
;     { const char* Qw = Pb + (size_t)(qb * 128 + wq * 32) * (INC * 2) + (C_DQ + c * 64) * 2; const unsigned qoff = (unsigned)((r32 * INC + hi * 8) * 2);
; #pragma unroll
;       for (int d0 = 0; d0 < 4; ++d0) qr[d0] = *reinterpret_cast<const bf16x8*>(Qw + qoff + d0 * 32); }
;     const int colB0 = c * 128;
;     const int krow = wid * 4 + (lane >> 4), kcc = (lane & 15) ^ (krow & 15);
;     const unsigned koff = (unsigned)((krow * INC + kcc * 8) * 2);
;     const int vkey = (wid >> 2) * 16 + (((wid >> 1) & 1) << 3) + (((lane >> 4) & 1) << 2) + ((lane >> 2) & 3)  , vcol = ((wid & 1) * 2 + (lane >> 5)) * 32 + (lane & 3) * 8;
;     const unsigned voff = (unsigned)((vkey * INC + vcol) * 2 + (C_DV - C_DK) * 2);
;     const int vb0 = (int)(uintptr_t)V_lds + v_rd_base(lane);
;     const char* Pk = Pb + (size_t)(t_lo * KVBLK) * (INC * 2) + C_DK * 2; int iposk = ipos - t_lo * KVBLK - 4 * hi; asm volatile("" : "+v"(iposk));     const int relw = t_lo * KVBLK - (qb * 128 + wq * 32);
;     typedef __attribute__((address_space(3))) unsigned lds_u32;
;     __attribute__((address_space(3))) unsigned char* ldsA = (__attribute__((address_space(3))) unsigned char*)lds + wid * 1024;
;     ...
;     f32x16 pA0, pA1, pB0, pB1; bf16x8 pa0, pa1, pa2, pa3; const int NT = nt;
;     STAGE(0); ENDI();
;     STAGE(1);
;     BIAS(pA0, pA1, 0); qkt<4>(pA0, pA1, K_lds, qr, r32, hi, colB0);
;     ...
;     if (c == 0) {
;     ...
;         const int lp_ = opaque_tid(wv) & 63, r32p = lp_ & 31, hip = lp_ >> 5;
;         exp_half(pA0);
.Lsym_entry:
	v_mov_b32_e32 v0, 0
	v_mov_b32_e32 v1, 0
	v_mov_b32_e32 v2, 0
	v_mov_b32_e32 v3, 0
	v_mov_b32_e32 v4, 0
	v_mov_b32_e32 v5, 0
	v_mov_b32_e32 v6, 0
	v_mov_b32_e32 v7, 0
	v_mov_b32_e32 v8, 0
	v_mov_b32_e32 v9, 0
	v_mov_b32_e32 v10, 0
	v_mov_b32_e32 v11, 0
	v_mov_b32_e32 v12, 0
	v_mov_b32_e32 v13, 0
	v_mov_b32_e32 v14, 0
	v_mov_b32_e32 v15, 0
	v_mov_b32_e32 v16, 0
	v_mov_b32_e32 v17, 0
	v_mov_b32_e32 v18, 0
	v_mov_b32_e32 v19, 0
	v_mov_b32_e32 v20, 0
	v_mov_b32_e32 v21, 0
	v_mov_b32_e32 v22, 0
	v_mov_b32_e32 v23, 0
	v_mov_b32_e32 v24, 0
	v_mov_b32_e32 v25, 0
	v_mov_b32_e32 v26, 0
	v_mov_b32_e32 v27, 0
	v_mov_b32_e32 v28, 0
	v_mov_b32_e32 v29, 0
	v_mov_b32_e32 v30, 0
	v_mov_b32_e32 v31, 0
	v_mov_b32_e32 v32, 0
	v_mov_b32_e32 v33, 0
	v_mov_b32_e32 v34, 0
	v_mov_b32_e32 v35, 0
	v_mov_b32_e32 v36, 0
	v_mov_b32_e32 v37, 0
	v_mov_b32_e32 v38, 0
	v_mov_b32_e32 v39, 0
	v_mov_b32_e32 v40, 0
	v_mov_b32_e32 v41, 0
	v_mov_b32_e32 v42, 0
	v_mov_b32_e32 v43, 0
	v_mov_b32_e32 v44, 0
	v_mov_b32_e32 v45, 0
	v_mov_b32_e32 v46, 0
	v_mov_b32_e32 v47, 0
	v_mov_b32_e32 v48, 0
	v_mov_b32_e32 v49, 0
	v_mov_b32_e32 v50, 0
	v_mov_b32_e32 v51, 0
	v_mov_b32_e32 v52, 0
	v_mov_b32_e32 v53, 0
	v_mov_b32_e32 v54, 0
	v_mov_b32_e32 v55, 0
	v_mov_b32_e32 v56, 0
	v_mov_b32_e32 v57, 0
	v_mov_b32_e32 v58, 0
	v_mov_b32_e32 v59, 0
	v_mov_b32_e32 v60, 0
	v_mov_b32_e32 v61, 0
	v_mov_b32_e32 v62, 0
	v_mov_b32_e32 v63, 0
	v_mov_b32_e32 v182, 0
	v_mbcnt_lo_u32_b32 v190, -1, 0
	v_mbcnt_hi_u32_b32 v190, -1, v190
	v_and_b32_e32 v191, 31, v190
	v_lshrrev_b32_e32 v187, 5, v190
	v_lshlrev_b32_e32 v185, 4, v187
	v_or_b32_e32 v185, s52, v185
	v_and_b32_e32 v183, 15, v191
	v_lshlrev_b32_e32 v183, 4, v183
	v_xor_b32_e32 v185, v185, v183
	v_lshlrev_b32_e32 v183, 8, v191
	v_xor_b32_e32 v178, 0, v185
	v_add_u32_e32 v178, v178, v183
	v_add_u32_e32 v178, 0x10000, v178
	v_xor_b32_e32 v179, 32, v185
	v_add_u32_e32 v179, v179, v183
	v_add_u32_e32 v179, 0x10000, v179
	v_xor_b32_e32 v180, 64, v185
	v_add_u32_e32 v180, v180, v183
	v_add_u32_e32 v180, 0x10000, v180
	v_xor_b32_e32 v181, 96, v185
	v_add_u32_e32 v181, v181, v183
	v_add_u32_e32 v181, 0x10000, v181
	s_add_i32 s55, s63, 64
	v_subrev_u32_e32 v183, 64, v236
	v_cvt_f32_i32_e32 v183, v183
	s_mov_b32 s54, 0
	s_add_u32 s56, s20, 0x1c1e00
	s_addc_u32 s57, s21, 0
	v_exp_f32_e32 v80, v80
	v_exp_f32_e32 v81, v81
	v_exp_f32_e32 v82, v82
	v_exp_f32_e32 v83, v83
	v_add_f32_e32 v182, v80, v182
	v_add_f32_e32 v182, v81, v182
	v_cvt_pk_bf16_f32 v128, v80, v81
	v_exp_f32_e32 v84, v84
	v_exp_f32_e32 v85, v85
	v_add_f32_e32 v182, v82, v182
	v_add_f32_e32 v182, v83, v182
	v_cvt_pk_bf16_f32 v129, v82, v83
	v_exp_f32_e32 v86, v86
	v_exp_f32_e32 v87, v87
	v_add_f32_e32 v182, v84, v182
	v_add_f32_e32 v182, v85, v182
	v_cvt_pk_bf16_f32 v130, v84, v85
	v_cvt_pk_bf16_f32 v131, v86, v87
	v_add_f32_e32 v182, v86, v182
	v_add_f32_e32 v182, v87, v182
	s_cmp_lt_i32 s55, 0
	s_cselect_b32 s100, -1.0, 1.0
	v_mul_f32_e32 v185, s100, v186
	s_add_i32 s100, s55, 62
	s_cmp_lt_u32 s100, 93
	s_cbranch_scc1 .Lsym_diag_n
	s_cmp_lt_i32 s55, 0
	s_cselect_b32 s100, -1.0, 1.0
	v_mul_f32_e32 v185, s100, v186
	v_fma_f32 v187, -v185, v183, s16
	v_fmamk_f32 v112, v185, 0x00000000, v187
	v_fmamk_f32 v96, v185, 0x42000000, v187
	v_fmamk_f32 v113, v185, 0x3f800000, v187
	v_fmamk_f32 v97, v185, 0x42040000, v187
	v_fmamk_f32 v114, v185, 0x40000000, v187
	v_fmamk_f32 v98, v185, 0x42080000, v187
	v_fmamk_f32 v115, v185, 0x40400000, v187
	v_fmamk_f32 v99, v185, 0x420c0000, v187
	v_fmamk_f32 v116, v185, 0x41000000, v187
	v_fmamk_f32 v100, v185, 0x42200000, v187
	v_fmamk_f32 v117, v185, 0x41100000, v187
	v_fmamk_f32 v101, v185, 0x42240000, v187
	v_fmamk_f32 v118, v185, 0x41200000, v187
	v_fmamk_f32 v102, v185, 0x42280000, v187
	v_fmamk_f32 v119, v185, 0x41300000, v187
	v_fmamk_f32 v103, v185, 0x422c0000, v187
	v_fmamk_f32 v120, v185, 0x41800000, v187
	v_fmamk_f32 v104, v185, 0x42400000, v187
	v_fmamk_f32 v121, v185, 0x41880000, v187
	v_fmamk_f32 v105, v185, 0x42440000, v187
	v_fmamk_f32 v122, v185, 0x41900000, v187
	v_fmamk_f32 v106, v185, 0x42480000, v187
	v_fmamk_f32 v123, v185, 0x41980000, v187
	v_fmamk_f32 v107, v185, 0x424c0000, v187
	v_fmamk_f32 v124, v185, 0x41c00000, v187
	v_fmamk_f32 v108, v185, 0x42600000, v187
	v_fmamk_f32 v125, v185, 0x41c80000, v187
	v_fmamk_f32 v109, v185, 0x42640000, v187
	v_fmamk_f32 v126, v185, 0x41d00000, v187
	v_fmamk_f32 v110, v185, 0x42680000, v187
	v_fmamk_f32 v127, v185, 0x41d80000, v187
	v_fmamk_f32 v111, v185, 0x426c0000, v187
	s_branch .Lsym_biasdone_n
.Lsym_diag_n:
	v_add_f32_e32 v190, 0x00000000, v183
	v_add_f32_e32 v191, 0xc2000000, v183
	v_fma_f32 v112, |v190|, v186, s16
	v_fma_f32 v96, |v191|, v186, s16
	v_add_f32_e32 v190, 0xbf800000, v183
	v_add_f32_e32 v191, 0xc2040000, v183
	v_fma_f32 v113, |v190|, v186, s16
	v_fma_f32 v97, |v191|, v186, s16
	v_add_f32_e32 v190, 0xc0000000, v183
	v_add_f32_e32 v191, 0xc2080000, v183
	v_fma_f32 v114, |v190|, v186, s16
	v_fma_f32 v98, |v191|, v186, s16
	v_add_f32_e32 v190, 0xc0400000, v183
	v_add_f32_e32 v191, 0xc20c0000, v183
	v_fma_f32 v115, |v190|, v186, s16
	v_fma_f32 v99, |v191|, v186, s16
	v_add_f32_e32 v190, 0xc1000000, v183
	v_add_f32_e32 v191, 0xc2200000, v183
	v_fma_f32 v116, |v190|, v186, s16
	v_fma_f32 v100, |v191|, v186, s16
	v_add_f32_e32 v190, 0xc1100000, v183
	v_add_f32_e32 v191, 0xc2240000, v183
	v_fma_f32 v117, |v190|, v186, s16
	v_fma_f32 v101, |v191|, v186, s16
	v_add_f32_e32 v190, 0xc1200000, v183
	v_add_f32_e32 v191, 0xc2280000, v183
	v_fma_f32 v118, |v190|, v186, s16
	v_fma_f32 v102, |v191|, v186, s16
	v_add_f32_e32 v190, 0xc1300000, v183
	v_add_f32_e32 v191, 0xc22c0000, v183
	v_fma_f32 v119, |v190|, v186, s16
	v_fma_f32 v103, |v191|, v186, s16
	v_add_f32_e32 v190, 0xc1800000, v183
	v_add_f32_e32 v191, 0xc2400000, v183
	v_fma_f32 v120, |v190|, v186, s16
	v_fma_f32 v104, |v191|, v186, s16
	v_add_f32_e32 v190, 0xc1880000, v183
	v_add_f32_e32 v191, 0xc2440000, v183
	v_fma_f32 v121, |v190|, v186, s16
	v_fma_f32 v105, |v191|, v186, s16
	v_add_f32_e32 v190, 0xc1900000, v183
	v_add_f32_e32 v191, 0xc2480000, v183
	v_fma_f32 v122, |v190|, v186, s16
	v_fma_f32 v106, |v191|, v186, s16
	v_add_f32_e32 v190, 0xc1980000, v183
	v_add_f32_e32 v191, 0xc24c0000, v183
	v_fma_f32 v123, |v190|, v186, s16
	v_fma_f32 v107, |v191|, v186, s16
	v_add_f32_e32 v190, 0xc1c00000, v183
	v_add_f32_e32 v191, 0xc2600000, v183
	v_fma_f32 v124, |v190|, v186, s16
	v_fma_f32 v108, |v191|, v186, s16
	v_add_f32_e32 v190, 0xc1c80000, v183
	v_add_f32_e32 v191, 0xc2640000, v183
	v_fma_f32 v125, |v190|, v186, s16
	v_fma_f32 v109, |v191|, v186, s16
	v_add_f32_e32 v190, 0xc1d00000, v183
	v_add_f32_e32 v191, 0xc2680000, v183
	v_fma_f32 v126, |v190|, v186, s16
	v_fma_f32 v110, |v191|, v186, s16
	v_add_f32_e32 v190, 0xc1d80000, v183
	v_add_f32_e32 v191, 0xc26c0000, v183
	v_fma_f32 v127, |v190|, v186, s16
	v_fma_f32 v111, |v191|, v186, s16
	v_mov_b32_e32 v185, v186

; template <int KS> __device__ __forceinline__ void pv_ks(f32x16* o, int vb, bf16x8 pa) {
;     const s16x4 l0 = tr_read<v_rd_off(0, KS, 0)>(vb), h0 = tr_read<v_rd_off(0, KS, 1)>(vb), l1 = tr_read<v_rd_off(1, KS, 0)>(vb), h1 = tr_read<v_rd_off(1, KS, 1)>(vb);
;     const s16x4 l2 = tr_read<v_rd_off(2, KS, 0)>(vb), h2 = tr_read<v_rd_off(2, KS, 1)>(vb), l3 = tr_read<v_rd_off(3, KS, 0)>(vb), h3 = tr_read<v_rd_off(3, KS, 1)>(vb);
;     ...
;     asm volatile("s_waitcnt lgkmcnt(6)" ::: "memory"); SBAR();
;     o[0] = __builtin_amdgcn_mfma_f32_32x32x16_bf16(pa, PK(l0, h0), o[0], 0, 0, 0);
;     asm volatile("s_waitcnt lgkmcnt(4)" ::: "memory"); SBAR();
;     o[1] = __builtin_amdgcn_mfma_f32_32x32x16_bf16(pa, PK(l1, h1), o[1], 0, 0, 0);
;     asm volatile("s_waitcnt lgkmcnt(2)" ::: "memory"); SBAR();
;     o[2] = __builtin_amdgcn_mfma_f32_32x32x16_bf16(pa, PK(l2, h2), o[2], 0, 0, 0);
;     asm volatile("s_waitcnt lgkmcnt(0)" ::: "memory"); SBAR();
;     o[3] = __builtin_amdgcn_mfma_f32_32x32x16_bf16(pa, PK(l3, h3), o[3], 0, 0, 0);
;     ...
; }
; __device__ __forceinline__ void pv_d0(f32x16* o, int vb, bf16x8 pa0, bf16x8 pa1, bf16x8 pa2, bf16x8 pa3) {
;     __builtin_amdgcn_s_setprio(1);
;     pv_ks<0>(o, vb, pa0); pv_ks<1>(o, vb, pa1); pv_ks<2>(o, vb, pa2); pv_ks<3>(o, vb, pa3);
;     __builtin_amdgcn_s_setprio(0);
; }
; __device__ __forceinline__ void exp_half(f32x16& p) {
; #pragma unroll
;     for (int r = 0; r < 16; ++r) p[r] = __builtin_amdgcn_exp2f(p[r]);
; }
; __device__ __forceinline__ void pack_p(const f32x16& p0, const f32x16& p1, float& l_reg, bf16x8& pa0, bf16x8& pa1, bf16x8& pa2, bf16x8& pa3) {
;     float ps = 0;
; #pragma unroll
;     for (int r = 0; r < 16; ++r) ps += p0[r];
; #pragma unroll
;     for (int r = 0; r < 16; ++r) ps += p1[r];
;     l_reg += ps;
;     ...
;     PK4(p0, 0, pa0); PK4(p0, 8, pa1); PK4(p1, 0, pa2); PK4(p1, 8, pa3);
;     ...
; }
; template <int ND0> __device__ __forceinline__ void qkt(f32x16& p0, f32x16& p1, const char* Ks, const bf16x8* qr, int r32, int hi, int colB0) {
; #pragma unroll
;     for (int d0 = 0; d0 < ND0; ++d0) { const int cb = colB0 + (d0 * 16 + hi * 8) * 2;
;         const bf16x8 b0 = *reinterpret_cast<const bf16x8*>(Ks + KSWZ(r32, cb));
;         const bf16x8 b1 = *reinterpret_cast<const bf16x8*>(Ks + KSWZ(32 + r32, cb));
;         p0 = __builtin_amdgcn_mfma_f32_32x32x16_bf16(b0, qr[d0], p0, 0, 0, 0);
.Lsym_nostage_s0:
	s_waitcnt lgkmcnt(14)
	v_mfma_f32_32x32x16_bf16 v[48:63], v[128:131], v[144:147], v[48:63]
	ds_read_b64_tr_b16 v[144:145], v252 offset:4096
	ds_read_b64_tr_b16 v[146:147], v252 offset:6144
	v_exp_f32_e32 v88, v88
	v_exp_f32_e32 v89, v89
	v_exp_f32_e32 v90, v90
	s_waitcnt lgkmcnt(14)
	v_mfma_f32_32x32x16_bf16 v[32:47], v[128:131], v[148:151], v[32:47]
	ds_read_b64_tr_b16 v[148:149], v252 offset:4608
	ds_read_b64_tr_b16 v[150:151], v252 offset:6656
	v_exp_f32_e32 v91, v91
	v_add_f32_e32 v182, v88, v182
	v_add_f32_e32 v182, v89, v182
	v_cvt_pk_bf16_f32 v132, v88, v89
	v_exp_f32_e32 v92, v92
	s_waitcnt lgkmcnt(11)
	v_mfma_f32_32x32x16_bf16 v[112:127], v[192:195], v[172:175], v[112:127]
	v_exp_f32_e32 v93, v93
	v_add_f32_e32 v182, v90, v182
	v_add_f32_e32 v182, v91, v182
	v_cvt_pk_bf16_f32 v133, v90, v91
	v_mfma_f32_32x32x16_bf16 v[16:31], v[128:131], v[152:155], v[16:31]
	ds_read_b64_tr_b16 v[152:153], v252 offset:5120
	ds_read_b64_tr_b16 v[154:155], v252 offset:7168
	v_exp_f32_e32 v94, v94
	v_exp_f32_e32 v95, v95
	v_add_f32_e32 v182, v92, v182
	v_add_f32_e32 v182, v93, v182
	s_waitcnt lgkmcnt(12)
	v_mfma_f32_32x32x16_bf16 v[96:111], v[196:199], v[172:175], v[96:111]
	v_cvt_pk_bf16_f32 v134, v92, v93
	v_cvt_pk_bf16_f32 v135, v94, v95
	v_add_f32_e32 v182, v94, v182
	v_add_f32_e32 v182, v95, v182
	v_exp_f32_e32 v64, v64
	v_mfma_f32_32x32x16_bf16 v[0:15], v[128:131], v[156:159], v[0:15]
	ds_read_b64_tr_b16 v[156:157], v252 offset:5632
	ds_read_b64_tr_b16 v[158:159], v252 offset:7680
	v_exp_f32_e32 v65, v65
	v_exp_f32_e32 v66, v66
	v_exp_f32_e32 v67, v67
	s_waitcnt lgkmcnt(13)
	v_mfma_f32_32x32x16_bf16 v[112:127], v[200:203], v[168:171], v[112:127]
	v_add_f32_e32 v182, v64, v182
	v_add_f32_e32 v182, v65, v182
	v_cvt_pk_bf16_f32 v136, v64, v65
	v_exp_f32_e32 v68, v68
	v_exp_f32_e32 v69, v69
	s_waitcnt lgkmcnt(6)
	v_mfma_f32_32x32x16_bf16 v[48:63], v[132:135], v[144:147], v[48:63]
	ds_read_b64_tr_b16 v[144:145], v252 offset:8192
	ds_read_b64_tr_b16 v[146:147], v252 offset:10240
	v_add_f32_e32 v182, v66, v182
	v_add_f32_e32 v182, v67, v182
	v_cvt_pk_bf16_f32 v137, v66, v67
	v_exp_f32_e32 v70, v70
	v_mfma_f32_32x32x16_bf16 v[96:111], v[204:207], v[168:171], v[96:111]
	v_exp_f32_e32 v71, v71
	v_add_f32_e32 v182, v68, v182
	v_add_f32_e32 v182, v69, v182
	v_cvt_pk_bf16_f32 v138, v68, v69
	v_cvt_pk_bf16_f32 v139, v70, v71
	s_waitcnt lgkmcnt(6)
	v_mfma_f32_32x32x16_bf16 v[32:47], v[132:135], v[148:151], v[32:47]
	ds_read_b64_tr_b16 v[148:149], v252 offset:8704
	ds_read_b64_tr_b16 v[150:151], v252 offset:10752
	v_add_f32_e32 v182, v70, v182
	v_add_f32_e32 v182, v71, v182
	v_exp_f32_e32 v72, v72
	v_exp_f32_e32 v73, v73
	v_mfma_f32_32x32x16_bf16 v[112:127], v[208:211], v[164:167], v[112:127]
	v_exp_f32_e32 v74, v74
	v_exp_f32_e32 v75, v75
	v_add_f32_e32 v182, v72, v182
	v_add_f32_e32 v182, v73, v182
	s_waitcnt lgkmcnt(6)
	v_mfma_f32_32x32x16_bf16 v[16:31], v[132:135], v[152:155], v[16:31]
	ds_read_b64_tr_b16 v[152:153], v252 offset:9216
	ds_read_b64_tr_b16 v[154:155], v252 offset:11264
	v_cvt_pk_bf16_f32 v140, v72, v73
	v_exp_f32_e32 v76, v76
	v_exp_f32_e32 v77, v77
	v_add_f32_e32 v182, v74, v182
	v_add_f32_e32 v182, v75, v182
	v_mfma_f32_32x32x16_bf16 v[96:111], v[212:215], v[164:167], v[96:111]
	v_cvt_pk_bf16_f32 v141, v74, v75
	v_exp_f32_e32 v78, v78
	v_exp_f32_e32 v79, v79
	v_add_f32_e32 v182, v76, v182
	s_waitcnt lgkmcnt(6)
	v_mfma_f32_32x32x16_bf16 v[0:15], v[132:135], v[156:159], v[0:15]
	ds_read_b64_tr_b16 v[156:157], v252 offset:9728
	ds_read_b64_tr_b16 v[158:159], v252 offset:11776
	v_add_f32_e32 v182, v77, v182
	v_cvt_pk_bf16_f32 v142, v76, v77
	v_cvt_pk_bf16_f32 v143, v78, v79
	v_add_f32_e32 v182, v78, v182
	v_add_f32_e32 v182, v79, v182
	v_fma_f32 v187, -v185, v183, s16
	v_mfma_f32_32x32x16_bf16 v[112:127], v[216:219], v[160:163], v[112:127]
	v_fmamk_f32 v80, v185, 0x00000000, v187
	v_fmamk_f32 v81, v185, 0x3f800000, v187
	v_fmamk_f32 v82, v185, 0x40000000, v187
	v_fmamk_f32 v83, v185, 0x40400000, v187
	v_fmamk_f32 v84, v185, 0x41000000, v187
	v_fmamk_f32 v85, v185, 0x41100000, v187
	v_mfma_f32_32x32x16_bf16 v[96:111], v[220:223], v[160:163], v[96:111]
	v_fmamk_f32 v86, v185, 0x41200000, v187
	v_fmamk_f32 v87, v185, 0x41300000, v187
	v_fmamk_f32 v88, v185, 0x41800000, v187
	v_fmamk_f32 v89, v185, 0x41880000, v187
	v_fmamk_f32 v90, v185, 0x41900000, v187
	v_fmamk_f32 v91, v185, 0x41980000, v187
	s_waitcnt lgkmcnt(6)
	v_mfma_f32_32x32x16_bf16 v[48:63], v[136:139], v[144:147], v[48:63]
	ds_read_b64_tr_b16 v[144:145], v252 offset:12288
	ds_read_b64_tr_b16 v[146:147], v252 offset:14336
	v_fmamk_f32 v92, v185, 0x41c00000, v187
	v_fmamk_f32 v93, v185, 0x41c80000, v187
	v_fmamk_f32 v94, v185, 0x41d00000, v187
	v_fmamk_f32 v95, v185, 0x41d80000, v187
	v_fmamk_f32 v64, v185, 0x42000000, v187
	v_fmamk_f32 v65, v185, 0x42040000, v187
	s_waitcnt lgkmcnt(6)
; #define PK4(P, BASE, OUT) do { u32x4 w = {cvtpk(P[BASE + 0], P[BASE + 1]), cvtpk(P[BASE + 2], P[BASE + 3]), cvtpk(P[BASE + 4], P[BASE + 5]), cvtpk(P[BASE + 6], P[BASE + 7])}; \
;     OUT = *reinterpret_cast<bf16x8*>(&w); } while (0)
; __device__ __forceinline__ void exp_half(f32x16& p) {
; #pragma unroll
;     for (int r = 0; r < 16; ++r) p[r] = __builtin_amdgcn_exp2f(p[r]);
; }
; __device__ __forceinline__ void pack_p(const f32x16& p0, const f32x16& p1, float& l_reg, bf16x8& pa0, bf16x8& pa1, bf16x8& pa2, bf16x8& pa3) {
;     float ps = 0;
; #pragma unroll
;     for (int r = 0; r < 16; ++r) ps += p0[r];
; #pragma unroll
;     for (int r = 0; r < 16; ++r) ps += p1[r];
;     l_reg += ps;
;     ...
;     PK4(p0, 0, pa0); PK4(p0, 8, pa1); PK4(p1, 0, pa2); PK4(p1, 8, pa3);
;     ...
; }
; template <int ND0> __device__ __forceinline__ void qkt(f32x16& p0, f32x16& p1, const char* Ks, const bf16x8* qr, int r32, int hi, int colB0) {
; #pragma unroll
;     for (int d0 = 0; d0 < ND0; ++d0) { const int cb = colB0 + (d0 * 16 + hi * 8) * 2;
;         const bf16x8 b0 = *reinterpret_cast<const bf16x8*>(Ks + KSWZ(r32, cb));
;         const bf16x8 b1 = *reinterpret_cast<const bf16x8*>(Ks + KSWZ(32 + r32, cb));
;         p0 = __builtin_amdgcn_mfma_f32_32x32x16_bf16(b0, qr[d0], p0, 0, 0, 0);
;         p1 = __builtin_amdgcn_mfma_f32_32x32x16_bf16(b1, qr[d0], p1, 0, 0, 0); }
; }
; __device__ __forceinline__ void bias_init(f32x16& p0, f32x16& p1, float base, float nslope2, float nM2, int rel  ) {
;     if (rel <= -63 || rel >= 31) {
;         const float sg = (rel < 0) ? -nslope2 : nslope2, lbv = fmaf(-sg, base, nM2);
; #pragma unroll
;         for (int r = 0; r < 16; ++r) { p0[r] = fmaf((float)((r & 3) + 8 * (r >> 2)), sg, lbv); p1[r] = fmaf((float)((r & 3) + 8 * (r >> 2) + 32), sg, lbv); }
;     } else {
; #pragma unroll
;         for (int r = 0; r < 16; ++r) { const float d = base - (float)((r & 3) + 8 * (r >> 2));
;             p0[r] = fmaf(fabsf(d), nslope2, nM2); p1[r] = fmaf(fabsf(d - 32.f), nslope2, nM2); }
;     }
; }
	v_mfma_f32_32x32x16_bf16 v[32:47], v[136:139], v[148:151], v[32:47]
	ds_read_b64_tr_b16 v[148:149], v252 offset:12800
	ds_read_b64_tr_b16 v[150:151], v252 offset:14848
	v_fmamk_f32 v66, v185, 0x42080000, v187
	v_fmamk_f32 v67, v185, 0x420c0000, v187
	v_fmamk_f32 v68, v185, 0x42200000, v187
	v_fmamk_f32 v69, v185, 0x42240000, v187
	v_fmamk_f32 v70, v185, 0x42280000, v187
	v_fmamk_f32 v71, v185, 0x422c0000, v187
	s_waitcnt lgkmcnt(6)
	v_mfma_f32_32x32x16_bf16 v[16:31], v[136:139], v[152:155], v[16:31]
	ds_read_b64_tr_b16 v[152:153], v252 offset:13312
	ds_read_b64_tr_b16 v[154:155], v252 offset:15360
	v_fmamk_f32 v72, v185, 0x42400000, v187
	v_fmamk_f32 v73, v185, 0x42440000, v187
	v_fmamk_f32 v74, v185, 0x42480000, v187
	v_fmamk_f32 v75, v185, 0x424c0000, v187
	v_fmamk_f32 v76, v185, 0x42600000, v187
	v_fmamk_f32 v77, v185, 0x42640000, v187
	s_waitcnt lgkmcnt(6)
	v_mfma_f32_32x32x16_bf16 v[0:15], v[136:139], v[156:159], v[0:15]
	ds_read_b64_tr_b16 v[156:157], v252 offset:13824
	ds_read_b64_tr_b16 v[158:159], v252 offset:15872
	v_fmamk_f32 v78, v185, 0x42680000, v187
	v_fmamk_f32 v79, v185, 0x426c0000, v187
	v_exp_f32_e32 v112, v112
	v_exp_f32_e32 v113, v113
	s_waitcnt lgkmcnt(6)
	v_mfma_f32_32x32x16_bf16 v[48:63], v[140:143], v[144:147], v[48:63]
	ds_read_b64_tr_b16 v[144:145], v252 offset:16384
	ds_read_b64_tr_b16 v[146:147], v252 offset:18432
	v_exp_f32_e32 v114, v114
	v_exp_f32_e32 v115, v115
	v_add_f32_e32 v182, v112, v182
	v_add_f32_e32 v182, v113, v182
	s_waitcnt lgkmcnt(6)
	v_mfma_f32_32x32x16_bf16 v[32:47], v[140:143], v[148:151], v[32:47]
	ds_read_b64_tr_b16 v[148:149], v252 offset:16896
	ds_read_b64_tr_b16 v[150:151], v252 offset:18944
	v_cvt_pk_bf16_f32 v128, v112, v113
	v_exp_f32_e32 v116, v116
	v_exp_f32_e32 v117, v117
	v_add_f32_e32 v182, v114, v182
	s_waitcnt lgkmcnt(6)
	v_mfma_f32_32x32x16_bf16 v[16:31], v[140:143], v[152:155], v[16:31]
	ds_read_b64_tr_b16 v[152:153], v252 offset:17408
	ds_read_b64_tr_b16 v[154:155], v252 offset:19456
	v_add_f32_e32 v182, v115, v182
	v_cvt_pk_bf16_f32 v129, v114, v115
	v_exp_f32_e32 v118, v118
	v_exp_f32_e32 v119, v119
	s_waitcnt lgkmcnt(6)
	v_mfma_f32_32x32x16_bf16 v[0:15], v[140:143], v[156:159], v[0:15]
	ds_read_b64_tr_b16 v[156:157], v252 offset:17920
	ds_read_b64_tr_b16 v[158:159], v252 offset:19968
	v_add_f32_e32 v182, v116, v182
	v_add_f32_e32 v182, v117, v182
	v_cvt_pk_bf16_f32 v130, v116, v117
	v_cvt_pk_bf16_f32 v131, v118, v119
	v_add_f32_e32 v182, v118, v182
	v_add_f32_e32 v182, v119, v182
	s_add_i32 s100, s55, 62
	s_cmp_lt_u32 s100, 93
	s_cbranch_scc0 .Lsym_nodiag_s0
	v_add_f32_e32 v190, 0x00000000, v183
	v_add_f32_e32 v191, 0xc2000000, v183
	v_fma_f32 v80, |v190|, v186, s16
	v_fma_f32 v64, |v191|, v186, s16
	v_add_f32_e32 v190, 0xbf800000, v183
	v_add_f32_e32 v191, 0xc2040000, v183
	v_fma_f32 v81, |v190|, v186, s16
	v_fma_f32 v65, |v191|, v186, s16
	v_add_f32_e32 v190, 0xc0000000, v183
	v_add_f32_e32 v191, 0xc2080000, v183
	v_fma_f32 v82, |v190|, v186, s16
	v_fma_f32 v66, |v191|, v186, s16
	v_add_f32_e32 v190, 0xc0400000, v183
	v_add_f32_e32 v191, 0xc20c0000, v183
	v_fma_f32 v83, |v190|, v186, s16
	v_fma_f32 v67, |v191|, v186, s16
	v_add_f32_e32 v190, 0xc1000000, v183
	v_add_f32_e32 v191, 0xc2200000, v183
	v_fma_f32 v84, |v190|, v186, s16
	v_fma_f32 v68, |v191|, v186, s16
	v_add_f32_e32 v190, 0xc1100000, v183
	v_add_f32_e32 v191, 0xc2240000, v183
	v_fma_f32 v85, |v190|, v186, s16
	v_fma_f32 v69, |v191|, v186, s16
	v_add_f32_e32 v190, 0xc1200000, v183
	v_add_f32_e32 v191, 0xc2280000, v183
	v_fma_f32 v86, |v190|, v186, s16
	v_fma_f32 v70, |v191|, v186, s16
	v_add_f32_e32 v190, 0xc1300000, v183
	v_add_f32_e32 v191, 0xc22c0000, v183
	v_fma_f32 v87, |v190|, v186, s16
	v_fma_f32 v71, |v191|, v186, s16
	v_add_f32_e32 v190, 0xc1800000, v183
	v_add_f32_e32 v191, 0xc2400000, v183
	v_fma_f32 v88, |v190|, v186, s16
	v_fma_f32 v72, |v191|, v186, s16
	v_add_f32_e32 v190, 0xc1880000, v183
	v_add_f32_e32 v191, 0xc2440000, v183
	v_fma_f32 v89, |v190|, v186, s16
	v_fma_f32 v73, |v191|, v186, s16
	v_add_f32_e32 v190, 0xc1900000, v183
	v_add_f32_e32 v191, 0xc2480000, v183
	v_fma_f32 v90, |v190|, v186, s16
	v_fma_f32 v74, |v191|, v186, s16
	v_add_f32_e32 v190, 0xc1980000, v183
	v_add_f32_e32 v191, 0xc24c0000, v183
	v_fma_f32 v91, |v190|, v186, s16
	v_fma_f32 v75, |v191|, v186, s16
	v_add_f32_e32 v190, 0xc1c00000, v183
	v_add_f32_e32 v191, 0xc2600000, v183
	v_fma_f32 v92, |v190|, v186, s16
	v_fma_f32 v76, |v191|, v186, s16
	v_add_f32_e32 v190, 0xc1c80000, v183
	v_add_f32_e32 v191, 0xc2640000, v183
	v_fma_f32 v93, |v190|, v186, s16
	v_fma_f32 v77, |v191|, v186, s16
	v_add_f32_e32 v190, 0xc1d00000, v183
	v_add_f32_e32 v191, 0xc2680000, v183
	v_fma_f32 v94, |v190|, v186, s16
	v_fma_f32 v78, |v191|, v186, s16
	v_add_f32_e32 v190, 0xc1d80000, v183
	v_add_f32_e32 v191, 0xc26c0000, v183
	v_fma_f32 v95, |v190|, v186, s16
	v_fma_f32 v79, |v191|, v186, s16
	v_mov_b32_e32 v185, v186

; template <int KS> __device__ __forceinline__ void pv_ks(f32x16* o, int vb, bf16x8 pa) {
;     const s16x4 l0 = tr_read<v_rd_off(0, KS, 0)>(vb), h0 = tr_read<v_rd_off(0, KS, 1)>(vb), l1 = tr_read<v_rd_off(1, KS, 0)>(vb), h1 = tr_read<v_rd_off(1, KS, 1)>(vb);
;     const s16x4 l2 = tr_read<v_rd_off(2, KS, 0)>(vb), h2 = tr_read<v_rd_off(2, KS, 1)>(vb), l3 = tr_read<v_rd_off(3, KS, 0)>(vb), h3 = tr_read<v_rd_off(3, KS, 1)>(vb);
;     ...
;     asm volatile("s_waitcnt lgkmcnt(6)" ::: "memory"); SBAR();
;     o[0] = __builtin_amdgcn_mfma_f32_32x32x16_bf16(pa, PK(l0, h0), o[0], 0, 0, 0);
;     asm volatile("s_waitcnt lgkmcnt(4)" ::: "memory"); SBAR();
;     o[1] = __builtin_amdgcn_mfma_f32_32x32x16_bf16(pa, PK(l1, h1), o[1], 0, 0, 0);
;     asm volatile("s_waitcnt lgkmcnt(2)" ::: "memory"); SBAR();
;     o[2] = __builtin_amdgcn_mfma_f32_32x32x16_bf16(pa, PK(l2, h2), o[2], 0, 0, 0);
;     asm volatile("s_waitcnt lgkmcnt(0)" ::: "memory"); SBAR();
;     o[3] = __builtin_amdgcn_mfma_f32_32x32x16_bf16(pa, PK(l3, h3), o[3], 0, 0, 0);
;     ...
; }
; __device__ __forceinline__ void pv_d0(f32x16* o, int vb, bf16x8 pa0, bf16x8 pa1, bf16x8 pa2, bf16x8 pa3) {
;     __builtin_amdgcn_s_setprio(1);
;     pv_ks<0>(o, vb, pa0); pv_ks<1>(o, vb, pa1); pv_ks<2>(o, vb, pa2); pv_ks<3>(o, vb, pa3);
;     __builtin_amdgcn_s_setprio(0);
; }
; __device__ __forceinline__ void exp_half(f32x16& p) {
; #pragma unroll
;     for (int r = 0; r < 16; ++r) p[r] = __builtin_amdgcn_exp2f(p[r]);
; }
; __device__ __forceinline__ void pack_p(const f32x16& p0, const f32x16& p1, float& l_reg, bf16x8& pa0, bf16x8& pa1, bf16x8& pa2, bf16x8& pa3) {
;     float ps = 0;
; #pragma unroll
;     for (int r = 0; r < 16; ++r) ps += p0[r];
; #pragma unroll
;     for (int r = 0; r < 16; ++r) ps += p1[r];
;     l_reg += ps;
;     ...
;     PK4(p0, 0, pa0); PK4(p0, 8, pa1); PK4(p1, 0, pa2); PK4(p1, 8, pa3);
;     ...
; }
; template <int ND0> __device__ __forceinline__ void qkt(f32x16& p0, f32x16& p1, const char* Ks, const bf16x8* qr, int r32, int hi, int colB0) {
; #pragma unroll
;     for (int d0 = 0; d0 < ND0; ++d0) { const int cb = colB0 + (d0 * 16 + hi * 8) * 2;
;         const bf16x8 b0 = *reinterpret_cast<const bf16x8*>(Ks + KSWZ(r32, cb));
;         const bf16x8 b1 = *reinterpret_cast<const bf16x8*>(Ks + KSWZ(32 + r32, cb));
;         p0 = __builtin_amdgcn_mfma_f32_32x32x16_bf16(b0, qr[d0], p0, 0, 0, 0);
.Lsym_nostage_s1:
	s_waitcnt lgkmcnt(14)
	v_mfma_f32_32x32x16_bf16 v[48:63], v[128:131], v[144:147], v[48:63]
	ds_read_b64_tr_b16 v[144:145], v252 offset:20480
	ds_read_b64_tr_b16 v[146:147], v252 offset:22528
	v_exp_f32_e32 v120, v120
	v_exp_f32_e32 v121, v121
	v_exp_f32_e32 v122, v122
	s_waitcnt lgkmcnt(14)
	v_mfma_f32_32x32x16_bf16 v[32:47], v[128:131], v[148:151], v[32:47]
	ds_read_b64_tr_b16 v[148:149], v252 offset:20992
	ds_read_b64_tr_b16 v[150:151], v252 offset:23040
	v_exp_f32_e32 v123, v123
	v_add_f32_e32 v182, v120, v182
	v_add_f32_e32 v182, v121, v182
	v_cvt_pk_bf16_f32 v132, v120, v121
	v_exp_f32_e32 v124, v124
	s_waitcnt lgkmcnt(11)
	v_mfma_f32_32x32x16_bf16 v[80:95], v[192:195], v[172:175], v[80:95]
	v_exp_f32_e32 v125, v125
	v_add_f32_e32 v182, v122, v182
	v_add_f32_e32 v182, v123, v182
	v_cvt_pk_bf16_f32 v133, v122, v123
	v_mfma_f32_32x32x16_bf16 v[16:31], v[128:131], v[152:155], v[16:31]
	ds_read_b64_tr_b16 v[152:153], v252 offset:21504
	ds_read_b64_tr_b16 v[154:155], v252 offset:23552
	v_exp_f32_e32 v126, v126
	v_exp_f32_e32 v127, v127
	v_add_f32_e32 v182, v124, v182
	v_add_f32_e32 v182, v125, v182
	s_waitcnt lgkmcnt(12)
	v_mfma_f32_32x32x16_bf16 v[64:79], v[196:199], v[172:175], v[64:79]
	v_cvt_pk_bf16_f32 v134, v124, v125
	v_cvt_pk_bf16_f32 v135, v126, v127
	v_add_f32_e32 v182, v126, v182
	v_add_f32_e32 v182, v127, v182
	v_exp_f32_e32 v96, v96
	v_mfma_f32_32x32x16_bf16 v[0:15], v[128:131], v[156:159], v[0:15]
	ds_read_b64_tr_b16 v[156:157], v252 offset:22016
	ds_read_b64_tr_b16 v[158:159], v252 offset:24064
	v_exp_f32_e32 v97, v97
	v_exp_f32_e32 v98, v98
	v_exp_f32_e32 v99, v99
	s_waitcnt lgkmcnt(13)
	v_mfma_f32_32x32x16_bf16 v[80:95], v[200:203], v[168:171], v[80:95]
	v_add_f32_e32 v182, v96, v182
	v_add_f32_e32 v182, v97, v182
	v_cvt_pk_bf16_f32 v136, v96, v97
	v_exp_f32_e32 v100, v100
	v_exp_f32_e32 v101, v101
	s_waitcnt lgkmcnt(6)
	v_mfma_f32_32x32x16_bf16 v[48:63], v[132:135], v[144:147], v[48:63]
	ds_read_b64_tr_b16 v[144:145], v252 offset:24576
	ds_read_b64_tr_b16 v[146:147], v252 offset:26624
	v_add_f32_e32 v182, v98, v182
	v_add_f32_e32 v182, v99, v182
	v_cvt_pk_bf16_f32 v137, v98, v99
	v_exp_f32_e32 v102, v102
	v_mfma_f32_32x32x16_bf16 v[64:79], v[204:207], v[168:171], v[64:79]
	v_exp_f32_e32 v103, v103
	v_add_f32_e32 v182, v100, v182
	v_add_f32_e32 v182, v101, v182
	v_cvt_pk_bf16_f32 v138, v100, v101
	v_cvt_pk_bf16_f32 v139, v102, v103
	s_waitcnt lgkmcnt(6)
	v_mfma_f32_32x32x16_bf16 v[32:47], v[132:135], v[148:151], v[32:47]
	ds_read_b64_tr_b16 v[148:149], v252 offset:25088
	ds_read_b64_tr_b16 v[150:151], v252 offset:27136
	v_add_f32_e32 v182, v102, v182
	v_add_f32_e32 v182, v103, v182
	v_exp_f32_e32 v104, v104
	v_exp_f32_e32 v105, v105
	v_mfma_f32_32x32x16_bf16 v[80:95], v[208:211], v[164:167], v[80:95]
	v_exp_f32_e32 v106, v106
	v_exp_f32_e32 v107, v107
	v_add_f32_e32 v182, v104, v182
	v_add_f32_e32 v182, v105, v182
	s_waitcnt lgkmcnt(6)
	v_mfma_f32_32x32x16_bf16 v[16:31], v[132:135], v[152:155], v[16:31]
	ds_read_b64_tr_b16 v[152:153], v252 offset:25600
	ds_read_b64_tr_b16 v[154:155], v252 offset:27648
	v_cvt_pk_bf16_f32 v140, v104, v105
	v_exp_f32_e32 v108, v108
	v_exp_f32_e32 v109, v109
	v_add_f32_e32 v182, v106, v182
	v_add_f32_e32 v182, v107, v182
	v_mfma_f32_32x32x16_bf16 v[64:79], v[212:215], v[164:167], v[64:79]
	v_cvt_pk_bf16_f32 v141, v106, v107
	v_exp_f32_e32 v110, v110
	v_exp_f32_e32 v111, v111
	v_add_f32_e32 v182, v108, v182
	s_waitcnt lgkmcnt(6)
	v_mfma_f32_32x32x16_bf16 v[0:15], v[132:135], v[156:159], v[0:15]
	ds_read_b64_tr_b16 v[156:157], v252 offset:26112
	ds_read_b64_tr_b16 v[158:159], v252 offset:28160
	v_add_f32_e32 v182, v109, v182
	v_cvt_pk_bf16_f32 v142, v108, v109
	v_cvt_pk_bf16_f32 v143, v110, v111
	v_add_f32_e32 v182, v110, v182
	v_add_f32_e32 v182, v111, v182
	v_fma_f32 v187, -v185, v183, s16
	v_mfma_f32_32x32x16_bf16 v[80:95], v[216:219], v[160:163], v[80:95]
	v_fmamk_f32 v112, v185, 0x00000000, v187
	v_fmamk_f32 v113, v185, 0x3f800000, v187
	v_fmamk_f32 v114, v185, 0x40000000, v187
	v_fmamk_f32 v115, v185, 0x40400000, v187
	v_fmamk_f32 v116, v185, 0x41000000, v187
	v_fmamk_f32 v117, v185, 0x41100000, v187
	v_mfma_f32_32x32x16_bf16 v[64:79], v[220:223], v[160:163], v[64:79]
	v_fmamk_f32 v118, v185, 0x41200000, v187
	v_fmamk_f32 v119, v185, 0x41300000, v187
	v_fmamk_f32 v120, v185, 0x41800000, v187
	v_fmamk_f32 v121, v185, 0x41880000, v187
	v_fmamk_f32 v122, v185, 0x41900000, v187
	v_fmamk_f32 v123, v185, 0x41980000, v187
	s_waitcnt lgkmcnt(6)
	v_mfma_f32_32x32x16_bf16 v[48:63], v[136:139], v[144:147], v[48:63]
	ds_read_b64_tr_b16 v[144:145], v252 offset:28672
	ds_read_b64_tr_b16 v[146:147], v252 offset:30720
	v_fmamk_f32 v124, v185, 0x41c00000, v187
	v_fmamk_f32 v125, v185, 0x41c80000, v187
	v_fmamk_f32 v126, v185, 0x41d00000, v187
	v_fmamk_f32 v127, v185, 0x41d80000, v187
	v_fmamk_f32 v96, v185, 0x42000000, v187
	v_fmamk_f32 v97, v185, 0x42040000, v187
	s_waitcnt lgkmcnt(6)
; #define PK4(P, BASE, OUT) do { u32x4 w = {cvtpk(P[BASE + 0], P[BASE + 1]), cvtpk(P[BASE + 2], P[BASE + 3]), cvtpk(P[BASE + 4], P[BASE + 5]), cvtpk(P[BASE + 6], P[BASE + 7])}; \
;     OUT = *reinterpret_cast<bf16x8*>(&w); } while (0)
; __device__ __forceinline__ void exp_half(f32x16& p) {
; #pragma unroll
;     for (int r = 0; r < 16; ++r) p[r] = __builtin_amdgcn_exp2f(p[r]);
; }
; __device__ __forceinline__ void pack_p(const f32x16& p0, const f32x16& p1, float& l_reg, bf16x8& pa0, bf16x8& pa1, bf16x8& pa2, bf16x8& pa3) {
;     float ps = 0;
; #pragma unroll
;     for (int r = 0; r < 16; ++r) ps += p0[r];
; #pragma unroll
;     for (int r = 0; r < 16; ++r) ps += p1[r];
;     l_reg += ps;
;     ...
;     PK4(p0, 0, pa0); PK4(p0, 8, pa1); PK4(p1, 0, pa2); PK4(p1, 8, pa3);
;     ...
; }
; template <int ND0> __device__ __forceinline__ void qkt(f32x16& p0, f32x16& p1, const char* Ks, const bf16x8* qr, int r32, int hi, int colB0) {
; #pragma unroll
;     for (int d0 = 0; d0 < ND0; ++d0) { const int cb = colB0 + (d0 * 16 + hi * 8) * 2;
;         const bf16x8 b0 = *reinterpret_cast<const bf16x8*>(Ks + KSWZ(r32, cb));
;         const bf16x8 b1 = *reinterpret_cast<const bf16x8*>(Ks + KSWZ(32 + r32, cb));
;         p0 = __builtin_amdgcn_mfma_f32_32x32x16_bf16(b0, qr[d0], p0, 0, 0, 0);
;         p1 = __builtin_amdgcn_mfma_f32_32x32x16_bf16(b1, qr[d0], p1, 0, 0, 0); }
; }
; __device__ __forceinline__ void bias_init(f32x16& p0, f32x16& p1, float base, float nslope2, float nM2, int rel  ) {
;     if (rel <= -63 || rel >= 31) {
;         const float sg = (rel < 0) ? -nslope2 : nslope2, lbv = fmaf(-sg, base, nM2);
; #pragma unroll
;         for (int r = 0; r < 16; ++r) { p0[r] = fmaf((float)((r & 3) + 8 * (r >> 2)), sg, lbv); p1[r] = fmaf((float)((r & 3) + 8 * (r >> 2) + 32), sg, lbv); }
;     } else {
; #pragma unroll
;         for (int r = 0; r < 16; ++r) { const float d = base - (float)((r & 3) + 8 * (r >> 2));
;             p0[r] = fmaf(fabsf(d), nslope2, nM2); p1[r] = fmaf(fabsf(d - 32.f), nslope2, nM2); }
;     }
; }
	v_mfma_f32_32x32x16_bf16 v[32:47], v[136:139], v[148:151], v[32:47]
	ds_read_b64_tr_b16 v[148:149], v252 offset:29184
	ds_read_b64_tr_b16 v[150:151], v252 offset:31232
	v_fmamk_f32 v98, v185, 0x42080000, v187
	v_fmamk_f32 v99, v185, 0x420c0000, v187
	v_fmamk_f32 v100, v185, 0x42200000, v187
	v_fmamk_f32 v101, v185, 0x42240000, v187
	v_fmamk_f32 v102, v185, 0x42280000, v187
	v_fmamk_f32 v103, v185, 0x422c0000, v187
	s_waitcnt lgkmcnt(6)
	v_mfma_f32_32x32x16_bf16 v[16:31], v[136:139], v[152:155], v[16:31]
	ds_read_b64_tr_b16 v[152:153], v252 offset:29696
	ds_read_b64_tr_b16 v[154:155], v252 offset:31744
	v_fmamk_f32 v104, v185, 0x42400000, v187
	v_fmamk_f32 v105, v185, 0x42440000, v187
	v_fmamk_f32 v106, v185, 0x42480000, v187
	v_fmamk_f32 v107, v185, 0x424c0000, v187
	v_fmamk_f32 v108, v185, 0x42600000, v187
	v_fmamk_f32 v109, v185, 0x42640000, v187
	s_waitcnt lgkmcnt(6)
	v_mfma_f32_32x32x16_bf16 v[0:15], v[136:139], v[156:159], v[0:15]
	ds_read_b64_tr_b16 v[156:157], v252 offset:30208
	ds_read_b64_tr_b16 v[158:159], v252 offset:32256
	v_fmamk_f32 v110, v185, 0x42680000, v187
	v_fmamk_f32 v111, v185, 0x426c0000, v187
	v_exp_f32_e32 v80, v80
	v_exp_f32_e32 v81, v81
	s_waitcnt lgkmcnt(6)
	v_mfma_f32_32x32x16_bf16 v[48:63], v[140:143], v[144:147], v[48:63]
	ds_read_b64_tr_b16 v[144:145], v252 offset:32768
	ds_read_b64_tr_b16 v[146:147], v252 offset:34816
	v_exp_f32_e32 v82, v82
	v_exp_f32_e32 v83, v83
	v_add_f32_e32 v182, v80, v182
	v_add_f32_e32 v182, v81, v182
	s_waitcnt lgkmcnt(6)
	v_mfma_f32_32x32x16_bf16 v[32:47], v[140:143], v[148:151], v[32:47]
	ds_read_b64_tr_b16 v[148:149], v252 offset:33280
	ds_read_b64_tr_b16 v[150:151], v252 offset:35328
	v_cvt_pk_bf16_f32 v128, v80, v81
	v_exp_f32_e32 v84, v84
	v_exp_f32_e32 v85, v85
	v_add_f32_e32 v182, v82, v182
	s_waitcnt lgkmcnt(6)
	v_mfma_f32_32x32x16_bf16 v[16:31], v[140:143], v[152:155], v[16:31]
	ds_read_b64_tr_b16 v[152:153], v252 offset:33792
	ds_read_b64_tr_b16 v[154:155], v252 offset:35840
	v_add_f32_e32 v182, v83, v182
	v_cvt_pk_bf16_f32 v129, v82, v83
	v_exp_f32_e32 v86, v86
	v_exp_f32_e32 v87, v87
	s_waitcnt lgkmcnt(6)
	v_mfma_f32_32x32x16_bf16 v[0:15], v[140:143], v[156:159], v[0:15]
	ds_read_b64_tr_b16 v[156:157], v252 offset:34304
	ds_read_b64_tr_b16 v[158:159], v252 offset:36352
	v_add_f32_e32 v182, v84, v182
	v_add_f32_e32 v182, v85, v182
	v_cvt_pk_bf16_f32 v130, v84, v85
	v_cvt_pk_bf16_f32 v131, v86, v87
	v_add_f32_e32 v182, v86, v182
	v_add_f32_e32 v182, v87, v182
	s_add_i32 s100, s55, 62
	s_cmp_lt_u32 s100, 93
	s_cbranch_scc0 .Lsym_nodiag_s1
	v_add_f32_e32 v190, 0x00000000, v183
	v_add_f32_e32 v191, 0xc2000000, v183
	v_fma_f32 v112, |v190|, v186, s16
	v_fma_f32 v96, |v191|, v186, s16
	v_add_f32_e32 v190, 0xbf800000, v183
	v_add_f32_e32 v191, 0xc2040000, v183
	v_fma_f32 v113, |v190|, v186, s16
	v_fma_f32 v97, |v191|, v186, s16
	v_add_f32_e32 v190, 0xc0000000, v183
	v_add_f32_e32 v191, 0xc2080000, v183
	v_fma_f32 v114, |v190|, v186, s16
	v_fma_f32 v98, |v191|, v186, s16
	v_add_f32_e32 v190, 0xc0400000, v183
	v_add_f32_e32 v191, 0xc20c0000, v183
	v_fma_f32 v115, |v190|, v186, s16
	v_fma_f32 v99, |v191|, v186, s16
	v_add_f32_e32 v190, 0xc1000000, v183
	v_add_f32_e32 v191, 0xc2200000, v183
	v_fma_f32 v116, |v190|, v186, s16
	v_fma_f32 v100, |v191|, v186, s16
	v_add_f32_e32 v190, 0xc1100000, v183
	v_add_f32_e32 v191, 0xc2240000, v183
	v_fma_f32 v117, |v190|, v186, s16
	v_fma_f32 v101, |v191|, v186, s16
	v_add_f32_e32 v190, 0xc1200000, v183
	v_add_f32_e32 v191, 0xc2280000, v183
	v_fma_f32 v118, |v190|, v186, s16
	v_fma_f32 v102, |v191|, v186, s16
	v_add_f32_e32 v190, 0xc1300000, v183
	v_add_f32_e32 v191, 0xc22c0000, v183
	v_fma_f32 v119, |v190|, v186, s16
	v_fma_f32 v103, |v191|, v186, s16
	v_add_f32_e32 v190, 0xc1800000, v183
	v_add_f32_e32 v191, 0xc2400000, v183
	v_fma_f32 v120, |v190|, v186, s16
	v_fma_f32 v104, |v191|, v186, s16
	v_add_f32_e32 v190, 0xc1880000, v183
	v_add_f32_e32 v191, 0xc2440000, v183
	v_fma_f32 v121, |v190|, v186, s16
	v_fma_f32 v105, |v191|, v186, s16
	v_add_f32_e32 v190, 0xc1900000, v183
	v_add_f32_e32 v191, 0xc2480000, v183
	v_fma_f32 v122, |v190|, v186, s16
	v_fma_f32 v106, |v191|, v186, s16
	v_add_f32_e32 v190, 0xc1980000, v183
	v_add_f32_e32 v191, 0xc24c0000, v183
	v_fma_f32 v123, |v190|, v186, s16
	v_fma_f32 v107, |v191|, v186, s16
	v_add_f32_e32 v190, 0xc1c00000, v183
	v_add_f32_e32 v191, 0xc2600000, v183
	v_fma_f32 v124, |v190|, v186, s16
	v_fma_f32 v108, |v191|, v186, s16
	v_add_f32_e32 v190, 0xc1c80000, v183
	v_add_f32_e32 v191, 0xc2640000, v183
	v_fma_f32 v125, |v190|, v186, s16
	v_fma_f32 v109, |v191|, v186, s16
	v_add_f32_e32 v190, 0xc1d00000, v183
	v_add_f32_e32 v191, 0xc2680000, v183
	v_fma_f32 v126, |v190|, v186, s16
	v_fma_f32 v110, |v191|, v186, s16
	v_add_f32_e32 v190, 0xc1d80000, v183
	v_add_f32_e32 v191, 0xc26c0000, v183
	v_fma_f32 v127, |v190|, v186, s16
	v_fma_f32 v111, |v191|, v186, s16
	v_mov_b32_e32 v185, v186

; template <int KS> __device__ __forceinline__ void pv_ks(f32x16* o, int vb, bf16x8 pa) {
;     const s16x4 l0 = tr_read<v_rd_off(0, KS, 0)>(vb), h0 = tr_read<v_rd_off(0, KS, 1)>(vb), l1 = tr_read<v_rd_off(1, KS, 0)>(vb), h1 = tr_read<v_rd_off(1, KS, 1)>(vb);
;     const s16x4 l2 = tr_read<v_rd_off(2, KS, 0)>(vb), h2 = tr_read<v_rd_off(2, KS, 1)>(vb), l3 = tr_read<v_rd_off(3, KS, 0)>(vb), h3 = tr_read<v_rd_off(3, KS, 1)>(vb);
;     ...
;     asm volatile("s_waitcnt lgkmcnt(6)" ::: "memory"); SBAR();
;     o[0] = __builtin_amdgcn_mfma_f32_32x32x16_bf16(pa, PK(l0, h0), o[0], 0, 0, 0);
;     asm volatile("s_waitcnt lgkmcnt(4)" ::: "memory"); SBAR();
;     o[1] = __builtin_amdgcn_mfma_f32_32x32x16_bf16(pa, PK(l1, h1), o[1], 0, 0, 0);
;     asm volatile("s_waitcnt lgkmcnt(2)" ::: "memory"); SBAR();
;     o[2] = __builtin_amdgcn_mfma_f32_32x32x16_bf16(pa, PK(l2, h2), o[2], 0, 0, 0);
;     asm volatile("s_waitcnt lgkmcnt(0)" ::: "memory"); SBAR();
;     o[3] = __builtin_amdgcn_mfma_f32_32x32x16_bf16(pa, PK(l3, h3), o[3], 0, 0, 0);
;     ...
; }
; __device__ __forceinline__ void pv_d0(f32x16* o, int vb, bf16x8 pa0, bf16x8 pa1, bf16x8 pa2, bf16x8 pa3) {
;     __builtin_amdgcn_s_setprio(1);
;     pv_ks<0>(o, vb, pa0); pv_ks<1>(o, vb, pa1); pv_ks<2>(o, vb, pa2); pv_ks<3>(o, vb, pa3);
;     __builtin_amdgcn_s_setprio(0);
; }
; __device__ __forceinline__ void exp_half(f32x16& p) {
; #pragma unroll
;     for (int r = 0; r < 16; ++r) p[r] = __builtin_amdgcn_exp2f(p[r]);
; }
; __device__ __forceinline__ void pack_p(const f32x16& p0, const f32x16& p1, float& l_reg, bf16x8& pa0, bf16x8& pa1, bf16x8& pa2, bf16x8& pa3) {
;     float ps = 0;
; #pragma unroll
;     for (int r = 0; r < 16; ++r) ps += p0[r];
; #pragma unroll
;     for (int r = 0; r < 16; ++r) ps += p1[r];
;     l_reg += ps;
;     ...
;     PK4(p0, 0, pa0); PK4(p0, 8, pa1); PK4(p1, 0, pa2); PK4(p1, 8, pa3);
;     ...
; }
; template <int ND0> __device__ __forceinline__ void qkt(f32x16& p0, f32x16& p1, const char* Ks, const bf16x8* qr, int r32, int hi, int colB0) {
; #pragma unroll
;     for (int d0 = 0; d0 < ND0; ++d0) { const int cb = colB0 + (d0 * 16 + hi * 8) * 2;
;         const bf16x8 b0 = *reinterpret_cast<const bf16x8*>(Ks + KSWZ(r32, cb));
;         const bf16x8 b1 = *reinterpret_cast<const bf16x8*>(Ks + KSWZ(32 + r32, cb));
;         p0 = __builtin_amdgcn_mfma_f32_32x32x16_bf16(b0, qr[d0], p0, 0, 0, 0);
.Lsym_nostage_s2:
	s_waitcnt lgkmcnt(14)
	v_mfma_f32_32x32x16_bf16 v[48:63], v[128:131], v[144:147], v[48:63]
	ds_read_b64_tr_b16 v[144:145], v252 offset:36864
	ds_read_b64_tr_b16 v[146:147], v252 offset:38912
	v_exp_f32_e32 v88, v88
	v_exp_f32_e32 v89, v89
	v_exp_f32_e32 v90, v90
	s_waitcnt lgkmcnt(14)
	v_mfma_f32_32x32x16_bf16 v[32:47], v[128:131], v[148:151], v[32:47]
	ds_read_b64_tr_b16 v[148:149], v252 offset:37376
	ds_read_b64_tr_b16 v[150:151], v252 offset:39424
	v_exp_f32_e32 v91, v91
	v_add_f32_e32 v182, v88, v182
	v_add_f32_e32 v182, v89, v182
	v_cvt_pk_bf16_f32 v132, v88, v89
	v_exp_f32_e32 v92, v92
	s_waitcnt lgkmcnt(11)
	v_mfma_f32_32x32x16_bf16 v[112:127], v[192:195], v[172:175], v[112:127]
	v_exp_f32_e32 v93, v93
	v_add_f32_e32 v182, v90, v182
	v_add_f32_e32 v182, v91, v182
	v_cvt_pk_bf16_f32 v133, v90, v91
	v_mfma_f32_32x32x16_bf16 v[16:31], v[128:131], v[152:155], v[16:31]
	ds_read_b64_tr_b16 v[152:153], v252 offset:37888
	ds_read_b64_tr_b16 v[154:155], v252 offset:39936
	v_exp_f32_e32 v94, v94
	v_exp_f32_e32 v95, v95
	v_add_f32_e32 v182, v92, v182
	v_add_f32_e32 v182, v93, v182
	s_waitcnt lgkmcnt(12)
	v_mfma_f32_32x32x16_bf16 v[96:111], v[196:199], v[172:175], v[96:111]
	v_cvt_pk_bf16_f32 v134, v92, v93
	v_cvt_pk_bf16_f32 v135, v94, v95
	v_add_f32_e32 v182, v94, v182
	v_add_f32_e32 v182, v95, v182
	v_exp_f32_e32 v64, v64
	v_mfma_f32_32x32x16_bf16 v[0:15], v[128:131], v[156:159], v[0:15]
	ds_read_b64_tr_b16 v[156:157], v252 offset:38400
	ds_read_b64_tr_b16 v[158:159], v252 offset:40448
	v_exp_f32_e32 v65, v65
	v_exp_f32_e32 v66, v66
	v_exp_f32_e32 v67, v67
	s_waitcnt lgkmcnt(13)
	v_mfma_f32_32x32x16_bf16 v[112:127], v[200:203], v[168:171], v[112:127]
	v_add_f32_e32 v182, v64, v182
	v_add_f32_e32 v182, v65, v182
	v_cvt_pk_bf16_f32 v136, v64, v65
	v_exp_f32_e32 v68, v68
	v_exp_f32_e32 v69, v69
	s_waitcnt lgkmcnt(6)
	v_mfma_f32_32x32x16_bf16 v[48:63], v[132:135], v[144:147], v[48:63]
	ds_read_b64_tr_b16 v[144:145], v252 offset:40960
	ds_read_b64_tr_b16 v[146:147], v252 offset:43008
	v_add_f32_e32 v182, v66, v182
	v_add_f32_e32 v182, v67, v182
	v_cvt_pk_bf16_f32 v137, v66, v67
	v_exp_f32_e32 v70, v70
	v_mfma_f32_32x32x16_bf16 v[96:111], v[204:207], v[168:171], v[96:111]
	v_exp_f32_e32 v71, v71
	v_add_f32_e32 v182, v68, v182
	v_add_f32_e32 v182, v69, v182
	v_cvt_pk_bf16_f32 v138, v68, v69
	v_cvt_pk_bf16_f32 v139, v70, v71
	s_waitcnt lgkmcnt(6)
	v_mfma_f32_32x32x16_bf16 v[32:47], v[132:135], v[148:151], v[32:47]
	ds_read_b64_tr_b16 v[148:149], v252 offset:41472
	ds_read_b64_tr_b16 v[150:151], v252 offset:43520
	v_add_f32_e32 v182, v70, v182
	v_add_f32_e32 v182, v71, v182
	v_exp_f32_e32 v72, v72
	v_exp_f32_e32 v73, v73
	v_mfma_f32_32x32x16_bf16 v[112:127], v[208:211], v[164:167], v[112:127]
	v_exp_f32_e32 v74, v74
	v_exp_f32_e32 v75, v75
	v_add_f32_e32 v182, v72, v182
	v_add_f32_e32 v182, v73, v182
	s_waitcnt lgkmcnt(6)
	v_mfma_f32_32x32x16_bf16 v[16:31], v[132:135], v[152:155], v[16:31]
	ds_read_b64_tr_b16 v[152:153], v252 offset:41984
	ds_read_b64_tr_b16 v[154:155], v252 offset:44032
	v_cvt_pk_bf16_f32 v140, v72, v73
	v_exp_f32_e32 v76, v76
	v_exp_f32_e32 v77, v77
	v_add_f32_e32 v182, v74, v182
	v_add_f32_e32 v182, v75, v182
	v_mfma_f32_32x32x16_bf16 v[96:111], v[212:215], v[164:167], v[96:111]
	v_cvt_pk_bf16_f32 v141, v74, v75
	v_exp_f32_e32 v78, v78
	v_exp_f32_e32 v79, v79
	v_add_f32_e32 v182, v76, v182
	s_waitcnt lgkmcnt(6)
	v_mfma_f32_32x32x16_bf16 v[0:15], v[132:135], v[156:159], v[0:15]
	ds_read_b64_tr_b16 v[156:157], v252 offset:42496
	ds_read_b64_tr_b16 v[158:159], v252 offset:44544
	v_add_f32_e32 v182, v77, v182
	v_cvt_pk_bf16_f32 v142, v76, v77
	v_cvt_pk_bf16_f32 v143, v78, v79
	v_add_f32_e32 v182, v78, v182
	v_add_f32_e32 v182, v79, v182
	v_fma_f32 v187, -v185, v183, s16
	v_mfma_f32_32x32x16_bf16 v[112:127], v[216:219], v[160:163], v[112:127]
	v_fmamk_f32 v80, v185, 0x00000000, v187
	v_fmamk_f32 v81, v185, 0x3f800000, v187
	v_fmamk_f32 v82, v185, 0x40000000, v187
	v_fmamk_f32 v83, v185, 0x40400000, v187
	v_fmamk_f32 v84, v185, 0x41000000, v187
	v_fmamk_f32 v85, v185, 0x41100000, v187
	v_mfma_f32_32x32x16_bf16 v[96:111], v[220:223], v[160:163], v[96:111]
	v_fmamk_f32 v86, v185, 0x41200000, v187
	v_fmamk_f32 v87, v185, 0x41300000, v187
	v_fmamk_f32 v88, v185, 0x41800000, v187
	v_fmamk_f32 v89, v185, 0x41880000, v187
	v_fmamk_f32 v90, v185, 0x41900000, v187
	v_fmamk_f32 v91, v185, 0x41980000, v187
	s_waitcnt lgkmcnt(6)
	v_mfma_f32_32x32x16_bf16 v[48:63], v[136:139], v[144:147], v[48:63]
	ds_read_b64_tr_b16 v[144:145], v252 offset:45056
	ds_read_b64_tr_b16 v[146:147], v252 offset:47104
	v_fmamk_f32 v92, v185, 0x41c00000, v187
	v_fmamk_f32 v93, v185, 0x41c80000, v187
	v_fmamk_f32 v94, v185, 0x41d00000, v187
	v_fmamk_f32 v95, v185, 0x41d80000, v187
	v_fmamk_f32 v64, v185, 0x42000000, v187
	v_fmamk_f32 v65, v185, 0x42040000, v187
	s_waitcnt lgkmcnt(6)
; #define PK4(P, BASE, OUT) do { u32x4 w = {cvtpk(P[BASE + 0], P[BASE + 1]), cvtpk(P[BASE + 2], P[BASE + 3]), cvtpk(P[BASE + 4], P[BASE + 5]), cvtpk(P[BASE + 6], P[BASE + 7])}; \
;     OUT = *reinterpret_cast<bf16x8*>(&w); } while (0)
; __device__ __forceinline__ void exp_half(f32x16& p) {
; #pragma unroll
;     for (int r = 0; r < 16; ++r) p[r] = __builtin_amdgcn_exp2f(p[r]);
; }
; __device__ __forceinline__ void pack_p(const f32x16& p0, const f32x16& p1, float& l_reg, bf16x8& pa0, bf16x8& pa1, bf16x8& pa2, bf16x8& pa3) {
;     float ps = 0;
; #pragma unroll
;     for (int r = 0; r < 16; ++r) ps += p0[r];
; #pragma unroll
;     for (int r = 0; r < 16; ++r) ps += p1[r];
;     l_reg += ps;
;     ...
;     PK4(p0, 0, pa0); PK4(p0, 8, pa1); PK4(p1, 0, pa2); PK4(p1, 8, pa3);
;     ...
; }
; template <int ND0> __device__ __forceinline__ void qkt(f32x16& p0, f32x16& p1, const char* Ks, const bf16x8* qr, int r32, int hi, int colB0) {
; #pragma unroll
;     for (int d0 = 0; d0 < ND0; ++d0) { const int cb = colB0 + (d0 * 16 + hi * 8) * 2;
;         const bf16x8 b0 = *reinterpret_cast<const bf16x8*>(Ks + KSWZ(r32, cb));
;         const bf16x8 b1 = *reinterpret_cast<const bf16x8*>(Ks + KSWZ(32 + r32, cb));
;         p0 = __builtin_amdgcn_mfma_f32_32x32x16_bf16(b0, qr[d0], p0, 0, 0, 0);
;         p1 = __builtin_amdgcn_mfma_f32_32x32x16_bf16(b1, qr[d0], p1, 0, 0, 0); }
; }
; __device__ __forceinline__ void bias_init(f32x16& p0, f32x16& p1, float base, float nslope2, float nM2, int rel  ) {
;     if (rel <= -63 || rel >= 31) {
;         const float sg = (rel < 0) ? -nslope2 : nslope2, lbv = fmaf(-sg, base, nM2);
; #pragma unroll
;         for (int r = 0; r < 16; ++r) { p0[r] = fmaf((float)((r & 3) + 8 * (r >> 2)), sg, lbv); p1[r] = fmaf((float)((r & 3) + 8 * (r >> 2) + 32), sg, lbv); }
;     } else {
; #pragma unroll
;         for (int r = 0; r < 16; ++r) { const float d = base - (float)((r & 3) + 8 * (r >> 2));
;             p0[r] = fmaf(fabsf(d), nslope2, nM2); p1[r] = fmaf(fabsf(d - 32.f), nslope2, nM2); }
;     }
; }
	v_mfma_f32_32x32x16_bf16 v[32:47], v[136:139], v[148:151], v[32:47]
	ds_read_b64_tr_b16 v[148:149], v252 offset:45568
	ds_read_b64_tr_b16 v[150:151], v252 offset:47616
	v_fmamk_f32 v66, v185, 0x42080000, v187
	v_fmamk_f32 v67, v185, 0x420c0000, v187
	v_fmamk_f32 v68, v185, 0x42200000, v187
	v_fmamk_f32 v69, v185, 0x42240000, v187
	v_fmamk_f32 v70, v185, 0x42280000, v187
	v_fmamk_f32 v71, v185, 0x422c0000, v187
	s_waitcnt lgkmcnt(6)
	v_mfma_f32_32x32x16_bf16 v[16:31], v[136:139], v[152:155], v[16:31]
	ds_read_b64_tr_b16 v[152:153], v252 offset:46080
	ds_read_b64_tr_b16 v[154:155], v252 offset:48128
	v_fmamk_f32 v72, v185, 0x42400000, v187
	v_fmamk_f32 v73, v185, 0x42440000, v187
	v_fmamk_f32 v74, v185, 0x42480000, v187
	v_fmamk_f32 v75, v185, 0x424c0000, v187
	v_fmamk_f32 v76, v185, 0x42600000, v187
	v_fmamk_f32 v77, v185, 0x42640000, v187
	s_waitcnt lgkmcnt(6)
	v_mfma_f32_32x32x16_bf16 v[0:15], v[136:139], v[156:159], v[0:15]
	ds_read_b64_tr_b16 v[156:157], v252 offset:46592
	ds_read_b64_tr_b16 v[158:159], v252 offset:48640
	v_fmamk_f32 v78, v185, 0x42680000, v187
	v_fmamk_f32 v79, v185, 0x426c0000, v187
	v_exp_f32_e32 v112, v112
	v_exp_f32_e32 v113, v113
	s_waitcnt lgkmcnt(6)
	v_mfma_f32_32x32x16_bf16 v[48:63], v[140:143], v[144:147], v[48:63]
	ds_read_b64_tr_b16 v[144:145], v252 offset:49152
	ds_read_b64_tr_b16 v[146:147], v252 offset:51200
	v_exp_f32_e32 v114, v114
	v_exp_f32_e32 v115, v115
	v_add_f32_e32 v182, v112, v182
	v_add_f32_e32 v182, v113, v182
	s_waitcnt lgkmcnt(6)
	v_mfma_f32_32x32x16_bf16 v[32:47], v[140:143], v[148:151], v[32:47]
	ds_read_b64_tr_b16 v[148:149], v252 offset:49664
	ds_read_b64_tr_b16 v[150:151], v252 offset:51712
	v_cvt_pk_bf16_f32 v128, v112, v113
	v_exp_f32_e32 v116, v116
	v_exp_f32_e32 v117, v117
	v_add_f32_e32 v182, v114, v182
	s_waitcnt lgkmcnt(6)
	v_mfma_f32_32x32x16_bf16 v[16:31], v[140:143], v[152:155], v[16:31]
	ds_read_b64_tr_b16 v[152:153], v252 offset:50176
	ds_read_b64_tr_b16 v[154:155], v252 offset:52224
	v_add_f32_e32 v182, v115, v182
	v_cvt_pk_bf16_f32 v129, v114, v115
	v_exp_f32_e32 v118, v118
	v_exp_f32_e32 v119, v119
	s_waitcnt lgkmcnt(6)
	v_mfma_f32_32x32x16_bf16 v[0:15], v[140:143], v[156:159], v[0:15]
	ds_read_b64_tr_b16 v[156:157], v252 offset:50688
	ds_read_b64_tr_b16 v[158:159], v252 offset:52736
	v_add_f32_e32 v182, v116, v182
	v_add_f32_e32 v182, v117, v182
	v_cvt_pk_bf16_f32 v130, v116, v117
	v_cvt_pk_bf16_f32 v131, v118, v119
	v_add_f32_e32 v182, v118, v182
	v_add_f32_e32 v182, v119, v182
	s_add_i32 s100, s55, 62
	s_cmp_lt_u32 s100, 93
	s_cbranch_scc0 .Lsym_nodiag_s2
	v_add_f32_e32 v190, 0x00000000, v183
	v_add_f32_e32 v191, 0xc2000000, v183
	v_fma_f32 v80, |v190|, v186, s16
	v_fma_f32 v64, |v191|, v186, s16
	v_add_f32_e32 v190, 0xbf800000, v183
	v_add_f32_e32 v191, 0xc2040000, v183
	v_fma_f32 v81, |v190|, v186, s16
	v_fma_f32 v65, |v191|, v186, s16
	v_add_f32_e32 v190, 0xc0000000, v183
	v_add_f32_e32 v191, 0xc2080000, v183
	v_fma_f32 v82, |v190|, v186, s16
	v_fma_f32 v66, |v191|, v186, s16
	v_add_f32_e32 v190, 0xc0400000, v183
	v_add_f32_e32 v191, 0xc20c0000, v183
	v_fma_f32 v83, |v190|, v186, s16
	v_fma_f32 v67, |v191|, v186, s16
	v_add_f32_e32 v190, 0xc1000000, v183
	v_add_f32_e32 v191, 0xc2200000, v183
	v_fma_f32 v84, |v190|, v186, s16
	v_fma_f32 v68, |v191|, v186, s16
	v_add_f32_e32 v190, 0xc1100000, v183
	v_add_f32_e32 v191, 0xc2240000, v183
	v_fma_f32 v85, |v190|, v186, s16
	v_fma_f32 v69, |v191|, v186, s16
	v_add_f32_e32 v190, 0xc1200000, v183
	v_add_f32_e32 v191, 0xc2280000, v183
	v_fma_f32 v86, |v190|, v186, s16
	v_fma_f32 v70, |v191|, v186, s16
	v_add_f32_e32 v190, 0xc1300000, v183
	v_add_f32_e32 v191, 0xc22c0000, v183
	v_fma_f32 v87, |v190|, v186, s16
	v_fma_f32 v71, |v191|, v186, s16
	v_add_f32_e32 v190, 0xc1800000, v183
	v_add_f32_e32 v191, 0xc2400000, v183
	v_fma_f32 v88, |v190|, v186, s16
	v_fma_f32 v72, |v191|, v186, s16
	v_add_f32_e32 v190, 0xc1880000, v183
	v_add_f32_e32 v191, 0xc2440000, v183
	v_fma_f32 v89, |v190|, v186, s16
	v_fma_f32 v73, |v191|, v186, s16
	v_add_f32_e32 v190, 0xc1900000, v183
	v_add_f32_e32 v191, 0xc2480000, v183
	v_fma_f32 v90, |v190|, v186, s16
	v_fma_f32 v74, |v191|, v186, s16
	v_add_f32_e32 v190, 0xc1980000, v183
	v_add_f32_e32 v191, 0xc24c0000, v183
	v_fma_f32 v91, |v190|, v186, s16
	v_fma_f32 v75, |v191|, v186, s16
	v_add_f32_e32 v190, 0xc1c00000, v183
	v_add_f32_e32 v191, 0xc2600000, v183
	v_fma_f32 v92, |v190|, v186, s16
	v_fma_f32 v76, |v191|, v186, s16
	v_add_f32_e32 v190, 0xc1c80000, v183
	v_add_f32_e32 v191, 0xc2640000, v183
	v_fma_f32 v93, |v190|, v186, s16
	v_fma_f32 v77, |v191|, v186, s16
	v_add_f32_e32 v190, 0xc1d00000, v183
	v_add_f32_e32 v191, 0xc2680000, v183
	v_fma_f32 v94, |v190|, v186, s16
	v_fma_f32 v78, |v191|, v186, s16
	v_add_f32_e32 v190, 0xc1d80000, v183
	v_add_f32_e32 v191, 0xc26c0000, v183
	v_fma_f32 v95, |v190|, v186, s16
	v_fma_f32 v79, |v191|, v186, s16
	v_mov_b32_e32 v185, v186

; template <int KS> __device__ __forceinline__ void pv_ks(f32x16* o, int vb, bf16x8 pa) {
;     const s16x4 l0 = tr_read<v_rd_off(0, KS, 0)>(vb), h0 = tr_read<v_rd_off(0, KS, 1)>(vb), l1 = tr_read<v_rd_off(1, KS, 0)>(vb), h1 = tr_read<v_rd_off(1, KS, 1)>(vb);
;     const s16x4 l2 = tr_read<v_rd_off(2, KS, 0)>(vb), h2 = tr_read<v_rd_off(2, KS, 1)>(vb), l3 = tr_read<v_rd_off(3, KS, 0)>(vb), h3 = tr_read<v_rd_off(3, KS, 1)>(vb);
;     ...
;     asm volatile("s_waitcnt lgkmcnt(6)" ::: "memory"); SBAR();
;     o[0] = __builtin_amdgcn_mfma_f32_32x32x16_bf16(pa, PK(l0, h0), o[0], 0, 0, 0);
;     asm volatile("s_waitcnt lgkmcnt(4)" ::: "memory"); SBAR();
;     o[1] = __builtin_amdgcn_mfma_f32_32x32x16_bf16(pa, PK(l1, h1), o[1], 0, 0, 0);
;     asm volatile("s_waitcnt lgkmcnt(2)" ::: "memory"); SBAR();
;     o[2] = __builtin_amdgcn_mfma_f32_32x32x16_bf16(pa, PK(l2, h2), o[2], 0, 0, 0);
;     asm volatile("s_waitcnt lgkmcnt(0)" ::: "memory"); SBAR();
;     o[3] = __builtin_amdgcn_mfma_f32_32x32x16_bf16(pa, PK(l3, h3), o[3], 0, 0, 0);
;     ...
; }
; __device__ __forceinline__ void pv_d0(f32x16* o, int vb, bf16x8 pa0, bf16x8 pa1, bf16x8 pa2, bf16x8 pa3) {
;     __builtin_amdgcn_s_setprio(1);
;     pv_ks<0>(o, vb, pa0); pv_ks<1>(o, vb, pa1); pv_ks<2>(o, vb, pa2); pv_ks<3>(o, vb, pa3);
;     __builtin_amdgcn_s_setprio(0);
; }
; __device__ __forceinline__ void exp_half(f32x16& p) {
; #pragma unroll
;     for (int r = 0; r < 16; ++r) p[r] = __builtin_amdgcn_exp2f(p[r]);
; }
; __device__ __forceinline__ void pack_p(const f32x16& p0, const f32x16& p1, float& l_reg, bf16x8& pa0, bf16x8& pa1, bf16x8& pa2, bf16x8& pa3) {
;     float ps = 0;
; #pragma unroll
;     for (int r = 0; r < 16; ++r) ps += p0[r];
; #pragma unroll
;     for (int r = 0; r < 16; ++r) ps += p1[r];
;     l_reg += ps;
;     ...
;     PK4(p0, 0, pa0); PK4(p0, 8, pa1); PK4(p1, 0, pa2); PK4(p1, 8, pa3);
;     ...
; }
; template <int ND0> __device__ __forceinline__ void qkt(f32x16& p0, f32x16& p1, const char* Ks, const bf16x8* qr, int r32, int hi, int colB0) {
; #pragma unroll
;     for (int d0 = 0; d0 < ND0; ++d0) { const int cb = colB0 + (d0 * 16 + hi * 8) * 2;
;         const bf16x8 b0 = *reinterpret_cast<const bf16x8*>(Ks + KSWZ(r32, cb));
;         const bf16x8 b1 = *reinterpret_cast<const bf16x8*>(Ks + KSWZ(32 + r32, cb));
;         p0 = __builtin_amdgcn_mfma_f32_32x32x16_bf16(b0, qr[d0], p0, 0, 0, 0);
.Lsym_nostage_s3:
	s_waitcnt lgkmcnt(14)
	v_mfma_f32_32x32x16_bf16 v[48:63], v[128:131], v[144:147], v[48:63]
	ds_read_b64_tr_b16 v[144:145], v252 offset:53248
	ds_read_b64_tr_b16 v[146:147], v252 offset:55296
	v_exp_f32_e32 v120, v120
	v_exp_f32_e32 v121, v121
	v_exp_f32_e32 v122, v122
	s_waitcnt lgkmcnt(14)
	v_mfma_f32_32x32x16_bf16 v[32:47], v[128:131], v[148:151], v[32:47]
	ds_read_b64_tr_b16 v[148:149], v252 offset:53760
	ds_read_b64_tr_b16 v[150:151], v252 offset:55808
	v_exp_f32_e32 v123, v123
	v_add_f32_e32 v182, v120, v182
	v_add_f32_e32 v182, v121, v182
	v_cvt_pk_bf16_f32 v132, v120, v121
	v_exp_f32_e32 v124, v124
	s_waitcnt lgkmcnt(11)
	v_mfma_f32_32x32x16_bf16 v[80:95], v[192:195], v[172:175], v[80:95]
	v_exp_f32_e32 v125, v125
	v_add_f32_e32 v182, v122, v182
	v_add_f32_e32 v182, v123, v182
	v_cvt_pk_bf16_f32 v133, v122, v123
	v_mfma_f32_32x32x16_bf16 v[16:31], v[128:131], v[152:155], v[16:31]
	ds_read_b64_tr_b16 v[152:153], v252 offset:54272
	ds_read_b64_tr_b16 v[154:155], v252 offset:56320
	v_exp_f32_e32 v126, v126
	v_exp_f32_e32 v127, v127
	v_add_f32_e32 v182, v124, v182
	v_add_f32_e32 v182, v125, v182
	s_waitcnt lgkmcnt(12)
	v_mfma_f32_32x32x16_bf16 v[64:79], v[196:199], v[172:175], v[64:79]
	v_cvt_pk_bf16_f32 v134, v124, v125
	v_cvt_pk_bf16_f32 v135, v126, v127
	v_add_f32_e32 v182, v126, v182
	v_add_f32_e32 v182, v127, v182
	v_exp_f32_e32 v96, v96
	v_mfma_f32_32x32x16_bf16 v[0:15], v[128:131], v[156:159], v[0:15]
	ds_read_b64_tr_b16 v[156:157], v252 offset:54784
	ds_read_b64_tr_b16 v[158:159], v252 offset:56832
	v_exp_f32_e32 v97, v97
	v_exp_f32_e32 v98, v98
	v_exp_f32_e32 v99, v99
	s_waitcnt lgkmcnt(13)
	v_mfma_f32_32x32x16_bf16 v[80:95], v[200:203], v[168:171], v[80:95]
	v_add_f32_e32 v182, v96, v182
	v_add_f32_e32 v182, v97, v182
	v_cvt_pk_bf16_f32 v136, v96, v97
	v_exp_f32_e32 v100, v100
	v_exp_f32_e32 v101, v101
	s_waitcnt lgkmcnt(6)
	v_mfma_f32_32x32x16_bf16 v[48:63], v[132:135], v[144:147], v[48:63]
	ds_read_b64_tr_b16 v[144:145], v252 offset:57344
	ds_read_b64_tr_b16 v[146:147], v252 offset:59392
	v_add_f32_e32 v182, v98, v182
	v_add_f32_e32 v182, v99, v182
	v_cvt_pk_bf16_f32 v137, v98, v99
	v_exp_f32_e32 v102, v102
	v_mfma_f32_32x32x16_bf16 v[64:79], v[204:207], v[168:171], v[64:79]
	v_exp_f32_e32 v103, v103
	v_add_f32_e32 v182, v100, v182
	v_add_f32_e32 v182, v101, v182
	v_cvt_pk_bf16_f32 v138, v100, v101
	v_cvt_pk_bf16_f32 v139, v102, v103
	s_waitcnt lgkmcnt(6)
	v_mfma_f32_32x32x16_bf16 v[32:47], v[132:135], v[148:151], v[32:47]
	ds_read_b64_tr_b16 v[148:149], v252 offset:57856
	ds_read_b64_tr_b16 v[150:151], v252 offset:59904
	v_add_f32_e32 v182, v102, v182
	v_add_f32_e32 v182, v103, v182
	v_exp_f32_e32 v104, v104
	v_exp_f32_e32 v105, v105
	v_mfma_f32_32x32x16_bf16 v[80:95], v[208:211], v[164:167], v[80:95]
	v_exp_f32_e32 v106, v106
	v_exp_f32_e32 v107, v107
	v_add_f32_e32 v182, v104, v182
	v_add_f32_e32 v182, v105, v182
	s_waitcnt lgkmcnt(6)
	v_mfma_f32_32x32x16_bf16 v[16:31], v[132:135], v[152:155], v[16:31]
	ds_read_b64_tr_b16 v[152:153], v252 offset:58368
	ds_read_b64_tr_b16 v[154:155], v252 offset:60416
	v_cvt_pk_bf16_f32 v140, v104, v105
	v_exp_f32_e32 v108, v108
	v_exp_f32_e32 v109, v109
	v_add_f32_e32 v182, v106, v182
	v_add_f32_e32 v182, v107, v182
	v_mfma_f32_32x32x16_bf16 v[64:79], v[212:215], v[164:167], v[64:79]
	v_cvt_pk_bf16_f32 v141, v106, v107
	v_exp_f32_e32 v110, v110
	v_exp_f32_e32 v111, v111
	v_add_f32_e32 v182, v108, v182
	s_waitcnt lgkmcnt(6)
	v_mfma_f32_32x32x16_bf16 v[0:15], v[132:135], v[156:159], v[0:15]
	ds_read_b64_tr_b16 v[156:157], v252 offset:58880
	ds_read_b64_tr_b16 v[158:159], v252 offset:60928
	v_add_f32_e32 v182, v109, v182
	v_cvt_pk_bf16_f32 v142, v108, v109
	v_cvt_pk_bf16_f32 v143, v110, v111
	v_add_f32_e32 v182, v110, v182
	v_add_f32_e32 v182, v111, v182
	v_fma_f32 v187, -v185, v183, s16
	v_mfma_f32_32x32x16_bf16 v[80:95], v[216:219], v[160:163], v[80:95]
	v_fmamk_f32 v112, v185, 0x00000000, v187
	v_fmamk_f32 v113, v185, 0x3f800000, v187
	v_fmamk_f32 v114, v185, 0x40000000, v187
	v_fmamk_f32 v115, v185, 0x40400000, v187
	v_fmamk_f32 v116, v185, 0x41000000, v187
	v_fmamk_f32 v117, v185, 0x41100000, v187
	v_mfma_f32_32x32x16_bf16 v[64:79], v[220:223], v[160:163], v[64:79]
	v_fmamk_f32 v118, v185, 0x41200000, v187
	v_fmamk_f32 v119, v185, 0x41300000, v187
	v_fmamk_f32 v120, v185, 0x41800000, v187
	v_fmamk_f32 v121, v185, 0x41880000, v187
	v_fmamk_f32 v122, v185, 0x41900000, v187
	v_fmamk_f32 v123, v185, 0x41980000, v187
	s_waitcnt lgkmcnt(6)
	v_mfma_f32_32x32x16_bf16 v[48:63], v[136:139], v[144:147], v[48:63]
	ds_read_b64_tr_b16 v[144:145], v252 offset:61440
	ds_read_b64_tr_b16 v[146:147], v252 offset:63488
	v_fmamk_f32 v124, v185, 0x41c00000, v187
	v_fmamk_f32 v125, v185, 0x41c80000, v187
	v_fmamk_f32 v126, v185, 0x41d00000, v187
	v_fmamk_f32 v127, v185, 0x41d80000, v187
	v_fmamk_f32 v96, v185, 0x42000000, v187
	v_fmamk_f32 v97, v185, 0x42040000, v187
	s_waitcnt lgkmcnt(6)
; #define PK4(P, BASE, OUT) do { u32x4 w = {cvtpk(P[BASE + 0], P[BASE + 1]), cvtpk(P[BASE + 2], P[BASE + 3]), cvtpk(P[BASE + 4], P[BASE + 5]), cvtpk(P[BASE + 6], P[BASE + 7])}; \
;     OUT = *reinterpret_cast<bf16x8*>(&w); } while (0)
; __device__ __forceinline__ void exp_half(f32x16& p) {
; #pragma unroll
;     for (int r = 0; r < 16; ++r) p[r] = __builtin_amdgcn_exp2f(p[r]);
; }
; __device__ __forceinline__ void pack_p(const f32x16& p0, const f32x16& p1, float& l_reg, bf16x8& pa0, bf16x8& pa1, bf16x8& pa2, bf16x8& pa3) {
;     float ps = 0;
; #pragma unroll
;     for (int r = 0; r < 16; ++r) ps += p0[r];
; #pragma unroll
;     for (int r = 0; r < 16; ++r) ps += p1[r];
;     l_reg += ps;
;     ...
;     PK4(p0, 0, pa0); PK4(p0, 8, pa1); PK4(p1, 0, pa2); PK4(p1, 8, pa3);
;     ...
; }
; template <int ND0> __device__ __forceinline__ void qkt(f32x16& p0, f32x16& p1, const char* Ks, const bf16x8* qr, int r32, int hi, int colB0) {
; #pragma unroll
;     for (int d0 = 0; d0 < ND0; ++d0) { const int cb = colB0 + (d0 * 16 + hi * 8) * 2;
;         const bf16x8 b0 = *reinterpret_cast<const bf16x8*>(Ks + KSWZ(r32, cb));
;         const bf16x8 b1 = *reinterpret_cast<const bf16x8*>(Ks + KSWZ(32 + r32, cb));
;         p0 = __builtin_amdgcn_mfma_f32_32x32x16_bf16(b0, qr[d0], p0, 0, 0, 0);
;         p1 = __builtin_amdgcn_mfma_f32_32x32x16_bf16(b1, qr[d0], p1, 0, 0, 0); }
; }
; __device__ __forceinline__ void bias_init(f32x16& p0, f32x16& p1, float base, float nslope2, float nM2, int rel  ) {
;     if (rel <= -63 || rel >= 31) {
;         const float sg = (rel < 0) ? -nslope2 : nslope2, lbv = fmaf(-sg, base, nM2);
; #pragma unroll
;         for (int r = 0; r < 16; ++r) { p0[r] = fmaf((float)((r & 3) + 8 * (r >> 2)), sg, lbv); p1[r] = fmaf((float)((r & 3) + 8 * (r >> 2) + 32), sg, lbv); }
;     } else {
; #pragma unroll
;         for (int r = 0; r < 16; ++r) { const float d = base - (float)((r & 3) + 8 * (r >> 2));
;             p0[r] = fmaf(fabsf(d), nslope2, nM2); p1[r] = fmaf(fabsf(d - 32.f), nslope2, nM2); }
;     }
; }
	v_mfma_f32_32x32x16_bf16 v[32:47], v[136:139], v[148:151], v[32:47]
	ds_read_b64_tr_b16 v[148:149], v252 offset:61952
	ds_read_b64_tr_b16 v[150:151], v252 offset:64000
	v_fmamk_f32 v98, v185, 0x42080000, v187
	v_fmamk_f32 v99, v185, 0x420c0000, v187
	v_fmamk_f32 v100, v185, 0x42200000, v187
	v_fmamk_f32 v101, v185, 0x42240000, v187
	v_fmamk_f32 v102, v185, 0x42280000, v187
	v_fmamk_f32 v103, v185, 0x422c0000, v187
	s_waitcnt lgkmcnt(6)
	v_mfma_f32_32x32x16_bf16 v[16:31], v[136:139], v[152:155], v[16:31]
	ds_read_b64_tr_b16 v[152:153], v252 offset:62464
	ds_read_b64_tr_b16 v[154:155], v252 offset:64512
	v_fmamk_f32 v104, v185, 0x42400000, v187
	v_fmamk_f32 v105, v185, 0x42440000, v187
	v_fmamk_f32 v106, v185, 0x42480000, v187
	v_fmamk_f32 v107, v185, 0x424c0000, v187
	v_fmamk_f32 v108, v185, 0x42600000, v187
	v_fmamk_f32 v109, v185, 0x42640000, v187
	s_waitcnt lgkmcnt(6)
	v_mfma_f32_32x32x16_bf16 v[0:15], v[136:139], v[156:159], v[0:15]
	ds_read_b64_tr_b16 v[156:157], v252 offset:62976
	ds_read_b64_tr_b16 v[158:159], v252 offset:65024
	v_fmamk_f32 v110, v185, 0x42680000, v187
	v_fmamk_f32 v111, v185, 0x426c0000, v187
	v_exp_f32_e32 v80, v80
	v_exp_f32_e32 v81, v81
	s_waitcnt lgkmcnt(6)
	v_mfma_f32_32x32x16_bf16 v[48:63], v[140:143], v[144:147], v[48:63]
	ds_read_b64_tr_b16 v[144:145], v252 offset:0
	ds_read_b64_tr_b16 v[146:147], v252 offset:2048
	v_exp_f32_e32 v82, v82
	v_exp_f32_e32 v83, v83
	v_add_f32_e32 v182, v80, v182
	v_add_f32_e32 v182, v81, v182
	s_waitcnt lgkmcnt(6)
	v_mfma_f32_32x32x16_bf16 v[32:47], v[140:143], v[148:151], v[32:47]
	ds_read_b64_tr_b16 v[148:149], v252 offset:512
	ds_read_b64_tr_b16 v[150:151], v252 offset:2560
	v_cvt_pk_bf16_f32 v128, v80, v81
	v_exp_f32_e32 v84, v84
	v_exp_f32_e32 v85, v85
	v_add_f32_e32 v182, v82, v182
	s_waitcnt lgkmcnt(6)
	v_mfma_f32_32x32x16_bf16 v[16:31], v[140:143], v[152:155], v[16:31]
	ds_read_b64_tr_b16 v[152:153], v252 offset:1024
	ds_read_b64_tr_b16 v[154:155], v252 offset:3072
	v_add_f32_e32 v182, v83, v182
	v_cvt_pk_bf16_f32 v129, v82, v83
	v_exp_f32_e32 v86, v86
	v_exp_f32_e32 v87, v87
	s_waitcnt lgkmcnt(6)
	v_mfma_f32_32x32x16_bf16 v[0:15], v[140:143], v[156:159], v[0:15]
	ds_read_b64_tr_b16 v[156:157], v252 offset:1536
	ds_read_b64_tr_b16 v[158:159], v252 offset:3584
	v_add_f32_e32 v182, v84, v182
	v_add_f32_e32 v182, v85, v182
	v_cvt_pk_bf16_f32 v130, v84, v85
	v_cvt_pk_bf16_f32 v131, v86, v87
	v_add_f32_e32 v182, v86, v182
	v_add_f32_e32 v182, v87, v182
	s_add_i32 s100, s55, 62
	s_cmp_lt_u32 s100, 93
	s_cbranch_scc0 .Lsym_nodiag_s3
	v_add_f32_e32 v190, 0x00000000, v183
	v_add_f32_e32 v191, 0xc2000000, v183
	v_fma_f32 v112, |v190|, v186, s16
	v_fma_f32 v96, |v191|, v186, s16
	v_add_f32_e32 v190, 0xbf800000, v183
	v_add_f32_e32 v191, 0xc2040000, v183
	v_fma_f32 v113, |v190|, v186, s16
	v_fma_f32 v97, |v191|, v186, s16
	v_add_f32_e32 v190, 0xc0000000, v183
	v_add_f32_e32 v191, 0xc2080000, v183
	v_fma_f32 v114, |v190|, v186, s16
	v_fma_f32 v98, |v191|, v186, s16
	v_add_f32_e32 v190, 0xc0400000, v183
	v_add_f32_e32 v191, 0xc20c0000, v183
	v_fma_f32 v115, |v190|, v186, s16
	v_fma_f32 v99, |v191|, v186, s16
	v_add_f32_e32 v190, 0xc1000000, v183
	v_add_f32_e32 v191, 0xc2200000, v183
	v_fma_f32 v116, |v190|, v186, s16
	v_fma_f32 v100, |v191|, v186, s16
	v_add_f32_e32 v190, 0xc1100000, v183
	v_add_f32_e32 v191, 0xc2240000, v183
	v_fma_f32 v117, |v190|, v186, s16
	v_fma_f32 v101, |v191|, v186, s16
	v_add_f32_e32 v190, 0xc1200000, v183
	v_add_f32_e32 v191, 0xc2280000, v183
	v_fma_f32 v118, |v190|, v186, s16
	v_fma_f32 v102, |v191|, v186, s16
	v_add_f32_e32 v190, 0xc1300000, v183
	v_add_f32_e32 v191, 0xc22c0000, v183
	v_fma_f32 v119, |v190|, v186, s16
	v_fma_f32 v103, |v191|, v186, s16
	v_add_f32_e32 v190, 0xc1800000, v183
	v_add_f32_e32 v191, 0xc2400000, v183
	v_fma_f32 v120, |v190|, v186, s16
	v_fma_f32 v104, |v191|, v186, s16
	v_add_f32_e32 v190, 0xc1880000, v183
	v_add_f32_e32 v191, 0xc2440000, v183
	v_fma_f32 v121, |v190|, v186, s16
	v_fma_f32 v105, |v191|, v186, s16
	v_add_f32_e32 v190, 0xc1900000, v183
	v_add_f32_e32 v191, 0xc2480000, v183
	v_fma_f32 v122, |v190|, v186, s16
	v_fma_f32 v106, |v191|, v186, s16
	v_add_f32_e32 v190, 0xc1980000, v183
	v_add_f32_e32 v191, 0xc24c0000, v183
	v_fma_f32 v123, |v190|, v186, s16
	v_fma_f32 v107, |v191|, v186, s16
	v_add_f32_e32 v190, 0xc1c00000, v183
	v_add_f32_e32 v191, 0xc2600000, v183
	v_fma_f32 v124, |v190|, v186, s16
	v_fma_f32 v108, |v191|, v186, s16
	v_add_f32_e32 v190, 0xc1c80000, v183
	v_add_f32_e32 v191, 0xc2640000, v183
	v_fma_f32 v125, |v190|, v186, s16
	v_fma_f32 v109, |v191|, v186, s16
	v_add_f32_e32 v190, 0xc1d00000, v183
	v_add_f32_e32 v191, 0xc2680000, v183
	v_fma_f32 v126, |v190|, v186, s16
	v_fma_f32 v110, |v191|, v186, s16
	v_add_f32_e32 v190, 0xc1d80000, v183
	v_add_f32_e32 v191, 0xc26c0000, v183
	v_fma_f32 v127, |v190|, v186, s16
	v_fma_f32 v111, |v191|, v186, s16
	v_mov_b32_e32 v185, v186
